# chainzz2 + code placement: one s_nop before the P1bf16/P4/P5 K-loop heads (8-byte phase 4 -> 0) and one after each loop so downstream code keeps its phase
# speedup vs baseline: 1.0012x; 1.0012x over previous
; #define PG8_STAGE(bufoff, gbase, voff) do { _Pragma("unroll") for (int _i = 0; _i < 2; ++_i) \
;         __builtin_amdgcn_global_load_lds((const unsigned*)((const char*)(gbase) + (voff)[_i]), (LAS unsigned*)(lds + (bufoff) + ldsw + _i * 8192), 16, 0, 0); } while (0)
; #define PG8_LDA(dst, b, h) do { _Pragma("unroll") for (int m = 0; m < 4; ++m) _Pragma("unroll") for (int k = 0; k < 2; ++k) dst[m][k] = *(const LAS bf16x8*)(lds + PG8_SA(b, h) + aoffk[k] + m * 2048); } while (0)
; #define PG8_LDB(dst, b, h) do { _Pragma("unroll") for (int n = 0; n < 2; ++n) _Pragma("unroll") for (int k = 0; k < 2; ++k) dst[n][k] = *(const LAS bf16x8*)(lds + PG8_SB(b, h) + boffk[k] + n * 2048); } while (0)
; #define PG8_WAIT_V(n) asm volatile("s_waitcnt vmcnt(" #n ")" ::: "memory")
; #define PG8_WAIT_L(n) asm volatile("s_waitcnt lgkmcnt(" #n ")" ::: "memory")
; #define PG8_BAR __builtin_amdgcn_s_barrier()
; #define PG8_SCHED __builtin_amdgcn_sched_barrier(0)
; template <class Epi, class Sched, class GemmT>
; __device__ __forceinline__ void gemm_phase(LAS unsigned char* lds, const GemmT& g, const Sched& S, const Epi& E, const int wid) {
;     ...
;             for (int t = 0; t < nt; t += 2) {
;                 const bool last = (t == nt - 2);
;                 const char* a1 = cA + (size_t)(t + 1) * kstep;
;                 const char* a2 = last ? ns.A : cA + (size_t)(t + 2) * kstep; const char* b2 = last ? ns.B : cB + (size_t)(t + 2) * kstep;
;                 const char* a3 = a2 + kstep; const char* b3 = b2 + kstep;
;                 unsigned vA2[2], vB2[2];
; #pragma unroll
;                 for (int i = 0; i < 2; ++i) { vA2[i] = last ? nvA[i] : voffA[i]; vB2[i] = last ? nvB[i] : voffB[i]; }
;                 const size_t hA2 = last ? nhA : hstepA, hB2 = last ? nhB : hstepB;
;                 PG8_LDB(B0, 0, 0); PG8_LDB(B1, 0, 1); PG8_SCHED; PG8_LDA(At, 0, 0); PG8_STAGE(PG8_SA(1, 1), a1 + hstepA, voffA);
;                 PG8_WAIT_V(8); PG8_WAIT_L(0); PG8_BAR; PG8_MMA(0, 0, At, B0); PG8_MMA(0, 1, At, B1); PG8_BAR; PG8_SCHED;
;     ...
; #pragma unroll
;         for (int a = 0; a < 2; ++a)
; #pragma unroll
;             for (int b = 0; b < 2; ++b)
; #pragma unroll
;                 for (int m = 0; m < 4; ++m)
; #pragma unroll
;                     for (int n = 0; n < 2; ++n) acc[a][b][m][n] = (f32x4){0.f, 0.f, 0.f, 0.f};
;         cur = nxt; ++ui;
.LBB0_416:
	s_ashr_i32 s71, s70, 31
	v_readlane_b32 s72, v254, 4
	s_ashr_i32 s59, s58, 31
	s_lshl_b64 s[36:37], s[70:71], 21
	v_readlane_b32 s76, v254, 8
	v_readlane_b32 s77, v254, 9
	s_add_u32 s56, s76, s36
	s_addc_u32 s57, s77, s37
	s_lshl_b64 s[58:59], s[58:59], 21
	v_readlane_b32 s26, v255, 7
	v_readlane_b32 s27, v255, 8
	s_add_u32 s5, s26, s58
	s_addc_u32 s16, s27, s59
	s_add_u32 s84, s84, 0x100080
	s_addc_u32 s85, s85, 0
	s_add_u32 s36, s19, s86
	v_mov_b32_e32 v0, 0
	s_addc_u32 s37, s34, s87
	s_mov_b32 s38, -2
	v_mov_b32_e32 v1, v0
	v_mov_b32_e32 v2, v0
	v_mov_b32_e32 v3, v0
	v_mov_b32_e32 v4, v0
	v_mov_b32_e32 v5, v0
	v_mov_b32_e32 v6, v0
	v_mov_b32_e32 v7, v0
	v_mov_b32_e32 v8, v0
	v_mov_b32_e32 v9, v0
	v_mov_b32_e32 v10, v0
	v_mov_b32_e32 v11, v0
	v_mov_b32_e32 v12, v0
	v_mov_b32_e32 v13, v0
	v_mov_b32_e32 v14, v0
	v_mov_b32_e32 v15, v0
	v_mov_b32_e32 v16, v0
	v_mov_b32_e32 v17, v0
	v_mov_b32_e32 v18, v0
	v_mov_b32_e32 v19, v0
	v_mov_b32_e32 v20, v0
	v_mov_b32_e32 v21, v0
	v_mov_b32_e32 v22, v0
	v_mov_b32_e32 v23, v0
	v_mov_b32_e32 v24, v0
	v_mov_b32_e32 v25, v0
	v_mov_b32_e32 v26, v0
	v_mov_b32_e32 v27, v0
	v_mov_b32_e32 v28, v0
	v_mov_b32_e32 v29, v0
	v_mov_b32_e32 v30, v0
	v_mov_b32_e32 v31, v0
	v_mov_b32_e32 v40, v0
	v_mov_b32_e32 v41, v0
	v_mov_b32_e32 v42, v0
	v_mov_b32_e32 v43, v0
	v_mov_b32_e32 v48, v0
	v_mov_b32_e32 v49, v0
	v_mov_b32_e32 v50, v0
	v_mov_b32_e32 v51, v0
	v_mov_b32_e32 v64, v0
	v_mov_b32_e32 v65, v0
	v_mov_b32_e32 v66, v0
	v_mov_b32_e32 v67, v0
	v_mov_b32_e32 v68, v0
	v_mov_b32_e32 v69, v0
	v_mov_b32_e32 v70, v0
	v_mov_b32_e32 v71, v0
	v_mov_b32_e32 v88, v0
	v_mov_b32_e32 v89, v0
	v_mov_b32_e32 v90, v0
	v_mov_b32_e32 v91, v0
	v_mov_b32_e32 v92, v0
	v_mov_b32_e32 v93, v0
	v_mov_b32_e32 v94, v0
	v_mov_b32_e32 v95, v0
	v_mov_b32_e32 v104, v0
	v_mov_b32_e32 v105, v0
	v_mov_b32_e32 v106, v0
	v_mov_b32_e32 v107, v0
	v_mov_b32_e32 v108, v0
	v_mov_b32_e32 v109, v0
	v_mov_b32_e32 v110, v0
	v_mov_b32_e32 v111, v0
	v_mov_b32_e32 v76, v0
	v_mov_b32_e32 v77, v0
	v_mov_b32_e32 v78, v0
	v_mov_b32_e32 v79, v0
	v_mov_b32_e32 v84, v0
	v_mov_b32_e32 v85, v0
	v_mov_b32_e32 v86, v0
	v_mov_b32_e32 v87, v0
	v_mov_b32_e32 v96, v0
	v_mov_b32_e32 v97, v0
	v_mov_b32_e32 v98, v0
	v_mov_b32_e32 v99, v0
	v_mov_b32_e32 v100, v0
	v_mov_b32_e32 v101, v0
	v_mov_b32_e32 v102, v0
	v_mov_b32_e32 v103, v0
	v_mov_b32_e32 v112, v0
	v_mov_b32_e32 v113, v0
	v_mov_b32_e32 v114, v0
	v_mov_b32_e32 v115, v0
	v_mov_b32_e32 v116, v0
	v_mov_b32_e32 v117, v0
	v_mov_b32_e32 v118, v0
	v_mov_b32_e32 v119, v0
	v_mov_b32_e32 v120, v0
	v_mov_b32_e32 v121, v0
	v_mov_b32_e32 v122, v0
	v_mov_b32_e32 v123, v0
	v_mov_b32_e32 v124, v0
	v_mov_b32_e32 v125, v0
	v_mov_b32_e32 v126, v0
	v_mov_b32_e32 v127, v0
	v_mov_b32_e32 v80, v0
	v_mov_b32_e32 v81, v0
	v_mov_b32_e32 v82, v0
	v_mov_b32_e32 v83, v0
	v_mov_b32_e32 v72, v0
	v_mov_b32_e32 v73, v0
	v_mov_b32_e32 v74, v0
	v_mov_b32_e32 v75, v0
	v_mov_b32_e32 v60, v0
	v_mov_b32_e32 v61, v0
	v_mov_b32_e32 v62, v0
	v_mov_b32_e32 v63, v0
	v_mov_b32_e32 v56, v0
	v_mov_b32_e32 v57, v0
	v_mov_b32_e32 v58, v0
	v_mov_b32_e32 v59, v0
	v_mov_b32_e32 v52, v0
	v_mov_b32_e32 v53, v0
	v_mov_b32_e32 v54, v0
	v_mov_b32_e32 v55, v0
	v_mov_b32_e32 v44, v0
	v_mov_b32_e32 v45, v0
	v_mov_b32_e32 v46, v0
	v_mov_b32_e32 v47, v0
	v_mov_b32_e32 v36, v0
	v_mov_b32_e32 v37, v0
	v_mov_b32_e32 v38, v0
	v_mov_b32_e32 v39, v0
	v_mov_b32_e32 v32, v0
	v_mov_b32_e32 v33, v0
	v_mov_b32_e32 v34, v0
	v_mov_b32_e32 v35, v0
	v_readlane_b32 s73, v254, 5
	v_readlane_b32 s74, v254, 6
	v_readlane_b32 s75, v254, 7
	v_readlane_b32 s78, v254, 10
	v_readlane_b32 s79, v254, 11
	s_nop 0
.LBB0_417:
	ds_read_b128 v[140:143], v192
	ds_read_b128 v[144:147], v193
	ds_read_b128 v[148:151], v194
	ds_read_b128 v[152:155], v195
	ds_read_b128 v[156:159], v196
	ds_read_b128 v[160:163], v197
	ds_read_b128 v[164:167], v198
	ds_read_b128 v[168:171], v199
	s_add_u32 s39, s84, 0xfff00080
	s_addc_u32 s40, s85, -1
	s_cmp_eq_u32 s38, 60
	s_cselect_b32 s87, s57, s40
	s_cselect_b32 s86, s56, s39
	s_cselect_b32 s71, s16, s37
	s_cselect_b32 s70, s5, s36
	v_lshl_add_u64 v[176:177], s[84:85], 0, v[128:129]
	s_add_i32 m0, s9, 0xc000
	ds_read_b128 v[172:175], v200
	ds_read_b128 v[208:211], v200 offset:2048
	ds_read_b128 v[212:215], v201
	ds_read_b128 v[216:219], v201 offset:2048
	ds_read_b128 v[220:223], v200 offset:4096
	ds_read_b128 v[224:227], v200 offset:6144
	ds_read_b128 v[230:233], v201 offset:4096
	ds_read_b128 v[234:237], v201 offset:6144
	global_load_lds_dwordx4 v[176:177], off
	v_lshl_add_u64 v[176:177], s[84:85], 0, v[132:133]
	s_add_i32 m0, s9, 0xe000
	s_nop 0
	global_load_lds_dwordx4 v[176:177], off
	s_waitcnt vmcnt(8)
	s_waitcnt lgkmcnt(0)
	s_barrier
; #define PG8_STAGE(bufoff, gbase, voff) do { _Pragma("unroll") for (int _i = 0; _i < 2; ++_i) \
;         __builtin_amdgcn_global_load_lds((const unsigned*)((const char*)(gbase) + (voff)[_i]), (LAS unsigned*)(lds + (bufoff) + ldsw + _i * 8192), 16, 0, 0); } while (0)
; #define PG8_LDA(dst, b, h) do { _Pragma("unroll") for (int m = 0; m < 4; ++m) _Pragma("unroll") for (int k = 0; k < 2; ++k) dst[m][k] = *(const LAS bf16x8*)(lds + PG8_SA(b, h) + aoffk[k] + m * 2048); } while (0)
; #define PG8_WAIT_V(n) asm volatile("s_waitcnt vmcnt(" #n ")" ::: "memory")
; #define PG8_WAIT_L(n) asm volatile("s_waitcnt lgkmcnt(" #n ")" ::: "memory")
; #define PG8_BAR __builtin_amdgcn_s_barrier()
; #define PG8_SCHED __builtin_amdgcn_sched_barrier(0)
; template <class Epi, class Sched, class GemmT>
; __device__ __forceinline__ void gemm_phase(LAS unsigned char* lds, const GemmT& g, const Sched& S, const Epi& E, const int wid) {
;     ...
;                 PG8_WAIT_V(8); PG8_WAIT_L(0); PG8_BAR; PG8_MMA(0, 0, At, B0); PG8_MMA(0, 1, At, B1); PG8_BAR; PG8_SCHED;
;                 PG8_LDA(At, 0, 1); PG8_STAGE(PG8_SB(0, 0), b2, vB2); PG8_STAGE(PG8_SB(0, 1), b2 + hB2, vB2); PG8_STAGE(PG8_SA(0, 0), a2, vA2);
;                 PG8_WAIT_V(8); PG8_WAIT_L(0); PG8_BAR; PG8_MMA(1, 0, At, B0); PG8_MMA(1, 1, At, B1); PG8_BAR; PG8_SCHED;
	s_setprio 3
	s_waitcnt lgkmcnt(0)
	v_mfma_f32_16x16x32_bf16 v[124:127], v[140:143], v[172:175], v[124:127]
	v_mfma_f32_16x16x32_bf16 v[124:127], v[144:147], v[212:215], v[124:127]
	v_mfma_f32_16x16x32_bf16 v[120:123], v[152:155], v[212:215], v[120:123]
	v_mfma_f32_16x16x32_bf16 v[120:123], v[148:151], v[172:175], v[120:123]
	v_mfma_f32_16x16x32_bf16 v[112:115], v[148:151], v[208:211], v[112:115]
	v_mfma_f32_16x16x32_bf16 v[112:115], v[152:155], v[216:219], v[112:115]
	v_mfma_f32_16x16x32_bf16 v[116:119], v[144:147], v[216:219], v[116:119]
	v_mfma_f32_16x16x32_bf16 v[116:119], v[140:143], v[208:211], v[116:119]
	v_mfma_f32_16x16x32_bf16 v[100:103], v[140:143], v[220:223], v[100:103]
	v_mfma_f32_16x16x32_bf16 v[100:103], v[144:147], v[230:233], v[100:103]
	v_mfma_f32_16x16x32_bf16 v[96:99], v[152:155], v[230:233], v[96:99]
	v_mfma_f32_16x16x32_bf16 v[96:99], v[148:151], v[220:223], v[96:99]
	v_mfma_f32_16x16x32_bf16 v[76:79], v[148:151], v[224:227], v[76:79]
	v_mfma_f32_16x16x32_bf16 v[76:79], v[152:155], v[234:237], v[76:79]
	v_mfma_f32_16x16x32_bf16 v[84:87], v[144:147], v[234:237], v[84:87]
	v_mfma_f32_16x16x32_bf16 v[84:87], v[140:143], v[224:227], v[84:87]
	s_setprio 0
	s_setprio 3
	v_mfma_f32_16x16x32_bf16 v[108:111], v[156:159], v[172:175], v[108:111]
	v_mfma_f32_16x16x32_bf16 v[108:111], v[160:163], v[212:215], v[108:111]
	v_mfma_f32_16x16x32_bf16 v[104:107], v[168:171], v[212:215], v[104:107]
	v_mfma_f32_16x16x32_bf16 v[104:107], v[164:167], v[172:175], v[104:107]
	v_mfma_f32_16x16x32_bf16 v[88:91], v[164:167], v[208:211], v[88:91]
	v_mfma_f32_16x16x32_bf16 v[88:91], v[168:171], v[216:219], v[88:91]
	v_mfma_f32_16x16x32_bf16 v[92:95], v[160:163], v[216:219], v[92:95]
	v_mfma_f32_16x16x32_bf16 v[92:95], v[156:159], v[208:211], v[92:95]
	v_mfma_f32_16x16x32_bf16 v[68:71], v[156:159], v[220:223], v[68:71]
	v_mfma_f32_16x16x32_bf16 v[68:71], v[160:163], v[230:233], v[68:71]
	v_mfma_f32_16x16x32_bf16 v[64:67], v[168:171], v[230:233], v[64:67]
	v_mfma_f32_16x16x32_bf16 v[64:67], v[164:167], v[220:223], v[64:67]
	v_mfma_f32_16x16x32_bf16 v[40:43], v[164:167], v[224:227], v[40:43]
	v_mfma_f32_16x16x32_bf16 v[40:43], v[168:171], v[234:237], v[40:43]
	v_mfma_f32_16x16x32_bf16 v[48:51], v[160:163], v[234:237], v[48:51]
	v_mfma_f32_16x16x32_bf16 v[48:51], v[156:159], v[224:227], v[48:51]
	s_setprio 0
	s_barrier
	s_add_i32 s39, s35, s68
	v_lshl_add_u64 v[176:177], s[70:71], 0, v[130:131]
	s_mov_b32 m0, s39
	ds_read_b128 v[172:175], v200 offset:16384
	ds_read_b128 v[208:211], v200 offset:18432
	ds_read_b128 v[212:215], v201 offset:16384
	ds_read_b128 v[216:219], v201 offset:18432
	ds_read_b128 v[220:223], v200 offset:20480
	ds_read_b128 v[224:227], v200 offset:22528
	ds_read_b128 v[230:233], v201 offset:20480
	ds_read_b128 v[234:237], v201 offset:22528
	global_load_lds_dwordx4 v[176:177], off
	s_add_i32 m0, s39, 0x2000
	s_add_u32 s40, s70, 0x100000
	v_lshl_add_u64 v[180:181], s[70:71], 0, v[134:135]
	s_addc_u32 s41, s71, 0
	s_add_i32 s39, s69, s68
	global_load_lds_dwordx4 v[180:181], off
	v_lshl_add_u64 v[184:185], s[40:41], 0, v[130:131]
	s_mov_b32 m0, s39
	v_lshl_add_u64 v[188:189], s[86:87], 0, v[132:133]
	global_load_lds_dwordx4 v[184:185], off
	v_lshl_add_u64 v[184:185], s[40:41], 0, v[134:135]
	s_add_i32 m0, s39, 0x2000
	s_nop 0
	global_load_lds_dwordx4 v[184:185], off
	v_lshl_add_u64 v[184:185], s[86:87], 0, v[128:129]
	s_mov_b32 m0, s9
	s_nop 0
	global_load_lds_dwordx4 v[184:185], off
	s_mov_b32 m0, s29
	s_nop 0
	global_load_lds_dwordx4 v[188:189], off
	s_waitcnt vmcnt(8)
	s_waitcnt lgkmcnt(0)
	s_barrier
	s_setprio 3
	s_waitcnt lgkmcnt(0)
	v_mfma_f32_16x16x32_bf16 v[28:31], v[140:143], v[172:175], v[28:31]
	v_mfma_f32_16x16x32_bf16 v[28:31], v[144:147], v[212:215], v[28:31]
	v_mfma_f32_16x16x32_bf16 v[24:27], v[152:155], v[212:215], v[24:27]
	v_mfma_f32_16x16x32_bf16 v[24:27], v[148:151], v[172:175], v[24:27]
	v_mfma_f32_16x16x32_bf16 v[16:19], v[148:151], v[208:211], v[16:19]
	v_mfma_f32_16x16x32_bf16 v[16:19], v[152:155], v[216:219], v[16:19]
	v_mfma_f32_16x16x32_bf16 v[20:23], v[144:147], v[216:219], v[20:23]
	v_mfma_f32_16x16x32_bf16 v[20:23], v[140:143], v[208:211], v[20:23]
	v_mfma_f32_16x16x32_bf16 v[12:15], v[140:143], v[220:223], v[12:15]
	v_mfma_f32_16x16x32_bf16 v[12:15], v[144:147], v[230:233], v[12:15]
	v_mfma_f32_16x16x32_bf16 v[8:11], v[152:155], v[230:233], v[8:11]
	v_mfma_f32_16x16x32_bf16 v[8:11], v[148:151], v[220:223], v[8:11]
	v_mfma_f32_16x16x32_bf16 v[0:3], v[148:151], v[224:227], v[0:3]
	v_mfma_f32_16x16x32_bf16 v[0:3], v[152:155], v[234:237], v[0:3]
	v_mfma_f32_16x16x32_bf16 v[4:7], v[144:147], v[234:237], v[4:7]
	v_mfma_f32_16x16x32_bf16 v[4:7], v[140:143], v[224:227], v[4:7]
	s_setprio 0
	s_setprio 3
	v_mfma_f32_16x16x32_bf16 v[80:83], v[156:159], v[172:175], v[80:83]
	v_mfma_f32_16x16x32_bf16 v[80:83], v[160:163], v[212:215], v[80:83]
	v_mfma_f32_16x16x32_bf16 v[72:75], v[168:171], v[212:215], v[72:75]
	v_mfma_f32_16x16x32_bf16 v[72:75], v[164:167], v[172:175], v[72:75]
	v_mfma_f32_16x16x32_bf16 v[56:59], v[164:167], v[208:211], v[56:59]
	v_mfma_f32_16x16x32_bf16 v[56:59], v[168:171], v[216:219], v[56:59]
	v_mfma_f32_16x16x32_bf16 v[60:63], v[160:163], v[216:219], v[60:63]
	v_mfma_f32_16x16x32_bf16 v[60:63], v[156:159], v[208:211], v[60:63]
	v_mfma_f32_16x16x32_bf16 v[52:55], v[156:159], v[220:223], v[52:55]
	v_mfma_f32_16x16x32_bf16 v[52:55], v[160:163], v[230:233], v[52:55]
	v_mfma_f32_16x16x32_bf16 v[44:47], v[168:171], v[230:233], v[44:47]
	v_mfma_f32_16x16x32_bf16 v[44:47], v[164:167], v[220:223], v[44:47]
	v_mfma_f32_16x16x32_bf16 v[32:35], v[164:167], v[224:227], v[32:35]
	v_mfma_f32_16x16x32_bf16 v[32:35], v[168:171], v[234:237], v[32:35]
	v_mfma_f32_16x16x32_bf16 v[36:39], v[160:163], v[234:237], v[36:39]
	v_mfma_f32_16x16x32_bf16 v[36:39], v[156:159], v[224:227], v[36:39]
	s_setprio 0
	s_barrier
; #define PG8_STAGE(bufoff, gbase, voff) do { _Pragma("unroll") for (int _i = 0; _i < 2; ++_i) \
;         __builtin_amdgcn_global_load_lds((const unsigned*)((const char*)(gbase) + (voff)[_i]), (LAS unsigned*)(lds + (bufoff) + ldsw + _i * 8192), 16, 0, 0); } while (0)
; #define PG8_LDA(dst, b, h) do { _Pragma("unroll") for (int m = 0; m < 4; ++m) _Pragma("unroll") for (int k = 0; k < 2; ++k) dst[m][k] = *(const LAS bf16x8*)(lds + PG8_SA(b, h) + aoffk[k] + m * 2048); } while (0)
; #define PG8_LDB(dst, b, h) do { _Pragma("unroll") for (int n = 0; n < 2; ++n) _Pragma("unroll") for (int k = 0; k < 2; ++k) dst[n][k] = *(const LAS bf16x8*)(lds + PG8_SB(b, h) + boffk[k] + n * 2048); } while (0)
; #define PG8_WAIT_V(n) asm volatile("s_waitcnt vmcnt(" #n ")" ::: "memory")
; #define PG8_WAIT_L(n) asm volatile("s_waitcnt lgkmcnt(" #n ")" ::: "memory")
; #define PG8_BAR __builtin_amdgcn_s_barrier()
; #define PG8_SCHED __builtin_amdgcn_sched_barrier(0)
; template <class Epi, class Sched, class GemmT>
; __device__ __forceinline__ void gemm_phase(LAS unsigned char* lds, const GemmT& g, const Sched& S, const Epi& E, const int wid) {
;     ...
;                 PG8_LDB(B0, 1, 0); PG8_LDB(B1, 1, 1); PG8_SCHED; PG8_LDA(At, 1, 0); PG8_STAGE(PG8_SA(0, 1), a2 + hA2, vA2);
;                 PG8_WAIT_V(8); PG8_WAIT_L(0); PG8_BAR; PG8_MMA(0, 0, At, B0); PG8_MMA(0, 1, At, B1); PG8_BAR; PG8_SCHED;
	s_add_i32 s39, 0, 0x18000
	s_add_i32 s48, 0, 0x1c000
	v_add_u32_e32 v140, s39, v187
	v_add_u32_e32 v144, s39, v190
	v_add_u32_e32 v156, s48, v187
	v_add_u32_e32 v160, s48, v190
	ds_read_b128 v[140:143], v140
	ds_read_b128 v[144:147], v144
	ds_read_b128 v[148:151], v202
	ds_read_b128 v[152:155], v203
	ds_read_b128 v[156:159], v156
	ds_read_b128 v[160:163], v160
	ds_read_b128 v[164:167], v204
	ds_read_b128 v[168:171], v205
	s_add_u32 s40, s86, 0x100000
	s_addc_u32 s41, s87, 0
	s_mov_b32 m0, s93
	v_lshl_add_u64 v[238:239], s[40:41], 0, v[128:129]
	ds_read_b128 v[172:175], v200 offset:32768
	ds_read_b128 v[208:211], v200 offset:34816
	ds_read_b128 v[212:215], v201 offset:32768
	ds_read_b128 v[216:219], v201 offset:34816
	ds_read_b128 v[220:223], v200 offset:36864
	ds_read_b128 v[224:227], v200 offset:38912
	ds_read_b128 v[230:233], v201 offset:36864
	ds_read_b128 v[234:237], v201 offset:38912
	global_load_lds_dwordx4 v[238:239], off
	v_lshl_add_u64 v[238:239], s[40:41], 0, v[132:133]
	s_mov_b32 m0, s6
	s_nop 0
	global_load_lds_dwordx4 v[238:239], off
	s_waitcnt vmcnt(8)
	s_waitcnt lgkmcnt(0)
	s_barrier
	s_setprio 3
	s_waitcnt lgkmcnt(0)
	v_mfma_f32_16x16x32_bf16 v[124:127], v[140:143], v[172:175], v[124:127]
	v_mfma_f32_16x16x32_bf16 v[124:127], v[144:147], v[212:215], v[124:127]
	v_mfma_f32_16x16x32_bf16 v[120:123], v[152:155], v[212:215], v[120:123]
	v_mfma_f32_16x16x32_bf16 v[120:123], v[148:151], v[172:175], v[120:123]
	v_mfma_f32_16x16x32_bf16 v[112:115], v[148:151], v[208:211], v[112:115]
	v_mfma_f32_16x16x32_bf16 v[112:115], v[152:155], v[216:219], v[112:115]
	v_mfma_f32_16x16x32_bf16 v[116:119], v[144:147], v[216:219], v[116:119]
	v_mfma_f32_16x16x32_bf16 v[116:119], v[140:143], v[208:211], v[116:119]
	v_mfma_f32_16x16x32_bf16 v[100:103], v[140:143], v[220:223], v[100:103]
	v_mfma_f32_16x16x32_bf16 v[100:103], v[144:147], v[230:233], v[100:103]
	v_mfma_f32_16x16x32_bf16 v[96:99], v[152:155], v[230:233], v[96:99]
	v_mfma_f32_16x16x32_bf16 v[96:99], v[148:151], v[220:223], v[96:99]
	v_mfma_f32_16x16x32_bf16 v[76:79], v[148:151], v[224:227], v[76:79]
	v_mfma_f32_16x16x32_bf16 v[76:79], v[152:155], v[234:237], v[76:79]
	v_mfma_f32_16x16x32_bf16 v[84:87], v[144:147], v[234:237], v[84:87]
	v_mfma_f32_16x16x32_bf16 v[84:87], v[140:143], v[224:227], v[84:87]
	s_setprio 0
	s_setprio 3
	v_mfma_f32_16x16x32_bf16 v[108:111], v[156:159], v[172:175], v[108:111]
	v_mfma_f32_16x16x32_bf16 v[108:111], v[160:163], v[212:215], v[108:111]
	v_mfma_f32_16x16x32_bf16 v[104:107], v[168:171], v[212:215], v[104:107]
	v_mfma_f32_16x16x32_bf16 v[104:107], v[164:167], v[172:175], v[104:107]
	v_mfma_f32_16x16x32_bf16 v[88:91], v[164:167], v[208:211], v[88:91]
	v_mfma_f32_16x16x32_bf16 v[88:91], v[168:171], v[216:219], v[88:91]
	v_mfma_f32_16x16x32_bf16 v[92:95], v[160:163], v[216:219], v[92:95]
	v_mfma_f32_16x16x32_bf16 v[92:95], v[156:159], v[208:211], v[92:95]
	v_mfma_f32_16x16x32_bf16 v[68:71], v[156:159], v[220:223], v[68:71]
	v_mfma_f32_16x16x32_bf16 v[68:71], v[160:163], v[230:233], v[68:71]
	v_mfma_f32_16x16x32_bf16 v[64:67], v[168:171], v[230:233], v[64:67]
	v_mfma_f32_16x16x32_bf16 v[64:67], v[164:167], v[220:223], v[64:67]
	v_mfma_f32_16x16x32_bf16 v[40:43], v[164:167], v[224:227], v[40:43]
	v_mfma_f32_16x16x32_bf16 v[40:43], v[168:171], v[234:237], v[40:43]
	v_mfma_f32_16x16x32_bf16 v[48:51], v[160:163], v[234:237], v[48:51]
	v_mfma_f32_16x16x32_bf16 v[48:51], v[156:159], v[224:227], v[48:51]
	s_setprio 0
	s_barrier
; #define PG8_STAGE(bufoff, gbase, voff) do { _Pragma("unroll") for (int _i = 0; _i < 2; ++_i) \
;         __builtin_amdgcn_global_load_lds((const unsigned*)((const char*)(gbase) + (voff)[_i]), (LAS unsigned*)(lds + (bufoff) + ldsw + _i * 8192), 16, 0, 0); } while (0)
; #define PG8_LDA(dst, b, h) do { _Pragma("unroll") for (int m = 0; m < 4; ++m) _Pragma("unroll") for (int k = 0; k < 2; ++k) dst[m][k] = *(const LAS bf16x8*)(lds + PG8_SA(b, h) + aoffk[k] + m * 2048); } while (0)
; #define PG8_WAIT_V(n) asm volatile("s_waitcnt vmcnt(" #n ")" ::: "memory")
; #define PG8_WAIT_L(n) asm volatile("s_waitcnt lgkmcnt(" #n ")" ::: "memory")
; #define PG8_BAR __builtin_amdgcn_s_barrier()
; #define PG8_SCHED __builtin_amdgcn_sched_barrier(0)
; template <class Epi, class Sched, class GemmT>
; __device__ __forceinline__ void gemm_phase(LAS unsigned char* lds, const GemmT& g, const Sched& S, const Epi& E, const int wid) {
;     ...
;                 PG8_LDA(At, 1, 1); PG8_STAGE(PG8_SB(1, 0), b3, vB2); PG8_STAGE(PG8_SB(1, 1), b3 + hB2, vB2); PG8_STAGE(PG8_SA(1, 0), a3, vA2);
;                 PG8_WAIT_V(8); PG8_WAIT_L(0); PG8_BAR; PG8_MMA(1, 0, At, B0); PG8_MMA(1, 1, At, B1); PG8_BAR; PG8_SCHED;
;             }
;             if constexpr (NSEG > 1) { if (sgi + 1 < NSEG) E.mid(acc, cur, sgi, wr, wc, fr, fq); }
;             cs = ns; cA = ns.A; cB = ns.B; hstepA = nhA; hstepB = nhB;
; #pragma unroll
;             for (int i = 0; i < 2; ++i) { voffA[i] = nvA[i]; voffB[i] = nvB[i]; }
	s_add_i32 s39, s39, s68
	v_lshl_add_u64 v[176:177], v[176:177], 0, s[66:67]
	s_mov_b32 m0, s39
	ds_read_b128 v[172:175], v200 offset:49152
	ds_read_b128 v[208:211], v200 offset:51200
	ds_read_b128 v[212:215], v201 offset:49152
	ds_read_b128 v[216:219], v201 offset:51200
	ds_read_b128 v[220:223], v200 offset:53248
	ds_read_b128 v[224:227], v200 offset:55296
	ds_read_b128 v[230:233], v201 offset:53248
	ds_read_b128 v[234:237], v201 offset:55296
	global_load_lds_dwordx4 v[176:177], off
	s_add_i32 m0, s39, 0x2000
	s_add_u32 s40, s70, 0x100080
	v_lshl_add_u64 v[176:177], v[180:181], 0, s[66:67]
	s_addc_u32 s41, s71, 0
	s_add_i32 s39, s48, s68
	global_load_lds_dwordx4 v[176:177], off
	v_lshl_add_u64 v[176:177], s[40:41], 0, v[130:131]
	s_mov_b32 m0, s39
	s_nop 0
	global_load_lds_dwordx4 v[176:177], off
	v_lshl_add_u64 v[176:177], s[40:41], 0, v[134:135]
	s_add_i32 m0, s39, 0x2000
	s_nop 0
	global_load_lds_dwordx4 v[176:177], off
	v_lshl_add_u64 v[176:177], v[184:185], 0, s[66:67]
	s_mov_b32 m0, s7
	s_nop 0
	global_load_lds_dwordx4 v[176:177], off
	v_lshl_add_u64 v[176:177], v[188:189], 0, s[66:67]
	s_mov_b32 m0, s12
	s_nop 0
	global_load_lds_dwordx4 v[176:177], off
	s_waitcnt vmcnt(8)
	s_waitcnt lgkmcnt(0)
	s_barrier
	s_setprio 3
	s_waitcnt lgkmcnt(0)
	v_mfma_f32_16x16x32_bf16 v[28:31], v[140:143], v[172:175], v[28:31]
	v_mfma_f32_16x16x32_bf16 v[28:31], v[144:147], v[212:215], v[28:31]
	v_mfma_f32_16x16x32_bf16 v[24:27], v[152:155], v[212:215], v[24:27]
	v_mfma_f32_16x16x32_bf16 v[24:27], v[148:151], v[172:175], v[24:27]
	v_mfma_f32_16x16x32_bf16 v[16:19], v[148:151], v[208:211], v[16:19]
	v_mfma_f32_16x16x32_bf16 v[16:19], v[152:155], v[216:219], v[16:19]
	v_mfma_f32_16x16x32_bf16 v[20:23], v[144:147], v[216:219], v[20:23]
	v_mfma_f32_16x16x32_bf16 v[20:23], v[140:143], v[208:211], v[20:23]
	v_mfma_f32_16x16x32_bf16 v[12:15], v[140:143], v[220:223], v[12:15]
	v_mfma_f32_16x16x32_bf16 v[12:15], v[144:147], v[230:233], v[12:15]
	v_mfma_f32_16x16x32_bf16 v[8:11], v[152:155], v[230:233], v[8:11]
	v_mfma_f32_16x16x32_bf16 v[8:11], v[148:151], v[220:223], v[8:11]
	v_mfma_f32_16x16x32_bf16 v[0:3], v[148:151], v[224:227], v[0:3]
	v_mfma_f32_16x16x32_bf16 v[0:3], v[152:155], v[234:237], v[0:3]
	v_mfma_f32_16x16x32_bf16 v[4:7], v[144:147], v[234:237], v[4:7]
	v_mfma_f32_16x16x32_bf16 v[4:7], v[140:143], v[224:227], v[4:7]
	s_setprio 0
	s_setprio 3
	v_mfma_f32_16x16x32_bf16 v[80:83], v[156:159], v[172:175], v[80:83]
	v_mfma_f32_16x16x32_bf16 v[80:83], v[160:163], v[212:215], v[80:83]
	v_mfma_f32_16x16x32_bf16 v[72:75], v[168:171], v[212:215], v[72:75]
	v_mfma_f32_16x16x32_bf16 v[72:75], v[164:167], v[172:175], v[72:75]
	v_mfma_f32_16x16x32_bf16 v[56:59], v[164:167], v[208:211], v[56:59]
	v_mfma_f32_16x16x32_bf16 v[56:59], v[168:171], v[216:219], v[56:59]
	v_mfma_f32_16x16x32_bf16 v[60:63], v[160:163], v[216:219], v[60:63]
	v_mfma_f32_16x16x32_bf16 v[60:63], v[156:159], v[208:211], v[60:63]
	v_mfma_f32_16x16x32_bf16 v[52:55], v[156:159], v[220:223], v[52:55]
	v_mfma_f32_16x16x32_bf16 v[52:55], v[160:163], v[230:233], v[52:55]
	v_mfma_f32_16x16x32_bf16 v[44:47], v[168:171], v[230:233], v[44:47]
	v_mfma_f32_16x16x32_bf16 v[44:47], v[164:167], v[220:223], v[44:47]
	v_mfma_f32_16x16x32_bf16 v[32:35], v[164:167], v[224:227], v[32:35]
	v_mfma_f32_16x16x32_bf16 v[32:35], v[168:171], v[234:237], v[32:35]
	v_mfma_f32_16x16x32_bf16 v[36:39], v[160:163], v[234:237], v[36:39]
	v_mfma_f32_16x16x32_bf16 v[36:39], v[156:159], v[224:227], v[36:39]
	s_setprio 0
	s_barrier
	s_add_i32 s38, s38, 2
	s_add_u32 s84, s84, 0x100
	s_addc_u32 s85, s85, 0
	s_add_u32 s36, s36, 0x100
	s_addc_u32 s37, s37, 0
	s_cmp_gt_u32 s38, 61
	s_cbranch_scc0 .LBB0_417
	s_nop 0
	s_and_b64 vcc, exec, s[20:21]
	s_cbranch_vccz .LBB0_420
	s_barrier

; #define PG8_STAGE(bufoff, gbase, voff) do { _Pragma("unroll") for (int _i = 0; _i < 2; ++_i) \
;         __builtin_amdgcn_global_load_lds((const unsigned*)((const char*)(gbase) + (voff)[_i]), (LAS unsigned*)(lds + (bufoff) + ldsw + _i * 8192), 16, 0, 0); } while (0)
; #define PG8_LDA(dst, b, h) do { _Pragma("unroll") for (int m = 0; m < 4; ++m) _Pragma("unroll") for (int k = 0; k < 2; ++k) dst[m][k] = *(const LAS bf16x8*)(lds + PG8_SA(b, h) + aoffk[k] + m * 2048); } while (0)
; #define PG8_LDB(dst, b, h) do { _Pragma("unroll") for (int n = 0; n < 2; ++n) _Pragma("unroll") for (int k = 0; k < 2; ++k) dst[n][k] = *(const LAS bf16x8*)(lds + PG8_SB(b, h) + boffk[k] + n * 2048); } while (0)
; #define PG8_WAIT_V(n) asm volatile("s_waitcnt vmcnt(" #n ")" ::: "memory")
; #define PG8_WAIT_L(n) asm volatile("s_waitcnt lgkmcnt(" #n ")" ::: "memory")
; #define PG8_BAR __builtin_amdgcn_s_barrier()
; template <class Epi, class Sched, class GemmT>
; __device__ __forceinline__ void gemm_phase(LAS unsigned char* lds, const GemmT& g, const Sched& S, const Epi& E, const int wid) {
;     ...
;             const Seg ns = (sgi + 1 < NSEG) ? g.seg(cur, sgi + 1) : g.seg(has_next ? nxt : cur, 0);
;             unsigned nvA[2], nvB[2]; size_t nhA, nhB;
;             if constexpr (GemmT::UNIFORM) { nvA[0] = voffA[0]; nvA[1] = voffA[1]; nvB[0] = voffB[0]; nvB[1] = voffB[1]; nhA = hstepA; nhB = hstepB; }
;             else PG8_VOFFS(nvA, nvB, nhA, nhB, ns);
;             const int nt = cs.nt;
;             for (int t = 0; t < nt; t += 2) {
;                 const bool last = (t == nt - 2);
;                 const char* a1 = cA + (size_t)(t + 1) * kstep;
;                 const char* a2 = last ? ns.A : cA + (size_t)(t + 2) * kstep; const char* b2 = last ? ns.B : cB + (size_t)(t + 2) * kstep;
;                 const char* a3 = a2 + kstep; const char* b3 = b2 + kstep;
;                 unsigned vA2[2], vB2[2];
; #pragma unroll
;                 for (int i = 0; i < 2; ++i) { vA2[i] = last ? nvA[i] : voffA[i]; vB2[i] = last ? nvB[i] : voffB[i]; }
;                 const size_t hA2 = last ? nhA : hstepA, hB2 = last ? nhB : hstepB;
;                 PG8_LDB(B0, 0, 0); PG8_LDB(B1, 0, 1); PG8_SCHED; PG8_LDA(At, 0, 0); PG8_STAGE(PG8_SA(1, 1), a1 + hstepA, voffA);
;                 PG8_WAIT_V(8); PG8_WAIT_L(0); PG8_BAR; PG8_MMA(0, 0, At, B0); PG8_MMA(0, 1, At, B1); PG8_BAR; PG8_SCHED;
.LBB0_763:
	s_cmp_lg_u32 s83, 2
	s_cselect_b64 s[52:53], -1, 0
	s_cmp_eq_u32 s83, 0
	s_mov_b64 s[50:51], s[18:19]
	s_mov_b64 s[48:49], s[12:13]
	s_cselect_b32 s6, s39, s24
	s_cselect_b32 s13, s41, s25
	s_cselect_b32 s18, s16, s81
	s_cselect_b32 s19, s17, s86
	s_cmp_eq_u32 s83, 2
	s_movk_i32 s12, 0x800
	s_cselect_b32 s84, s12, 0x400
	s_cselect_b32 s12, s74, s40
	s_cselect_b32 s43, s88, s19
	s_cselect_b32 s58, s87, s18
	s_cselect_b32 s18, s75, s73
	s_cselect_b32 s59, s31, s13
	s_cselect_b32 s6, s30, s6
	s_cselect_b32 s60, 11, 10
	s_ashr_i32 s13, s12, 31
	s_lshl_b64 s[12:13], s[12:13], 8
	s_ashr_i32 s19, s18, 31
	s_lshl_b64 s[12:13], s[12:13], s60
	s_lshl_b64 s[56:57], s[18:19], 8
	s_lshl_b64 s[12:13], s[12:13], 1
	s_add_u32 s18, s58, s12
	s_addc_u32 s19, s43, s13
	s_lshl_b64 s[12:13], s[56:57], s60
	s_lshl_b64 s[12:13], s[12:13], 1
	s_add_u32 s12, s6, s12
	s_addc_u32 s13, s59, s13
	s_lshl_b32 s6, s84, 8
	s_add_u32 s85, s48, 0x100
	s_addc_u32 s89, s49, 0
	s_add_u32 s43, s50, s44
	v_lshlrev_b32_e32 v0, s60, v204
	s_addc_u32 s49, s51, s45
	v_add_lshl_u32 v190, v0, v191, 1
	v_lshlrev_b32_e32 v0, s60, v205
	s_add_u32 s48, s43, 0x80
	v_add_lshl_u32 v214, v0, v191, 1
	v_lshlrev_b32_e32 v0, s60, v206
	v_mov_b32_e32 v133, v1
	v_mov_b32_e32 v131, v1
	s_addc_u32 s49, s49, 0
	s_mov_b32 s43, s7
	v_add_lshl_u32 v194, v0, v193, 1
	v_lshlrev_b32_e32 v0, s60, v207
	v_lshl_add_u64 v[134:135], s[48:49], 0, v[132:133]
	v_lshl_add_u64 v[136:137], s[48:49], 0, v[130:131]
	s_lshl_b64 s[48:49], s[42:43], 7
	v_add_lshl_u32 v192, v0, v193, 1
	s_add_u32 s43, s48, 0xffffff00
	s_mov_b64 s[56:57], 0
	s_mov_b32 s90, 0
	s_nop 0
.LBB0_764:
	s_cmp_eq_u32 s43, s56
	s_cselect_b64 vcc, -1, 0
	s_add_i32 s90, s90, 2
	v_add_u32_e32 v131, s62, v208
	s_add_u32 s48, s50, s56
	v_add_u32_e32 v133, s62, v209
	ds_read_b128 v[144:147], v131
	ds_read_b128 v[148:151], v133
	v_add_u32_e32 v131, s63, v208
	s_addc_u32 s49, s51, s57
	v_add_u32_e32 v133, s63, v209
	ds_read_b128 v[152:155], v131
	ds_read_b128 v[156:159], v133
	v_add_u32_e32 v131, s64, v208
	s_add_u32 s58, s48, 0x100
	v_add_u32_e32 v133, s64, v209
	ds_read_b128 v[160:163], v131
	ds_read_b128 v[164:167], v133
	v_add_u32_e32 v131, s65, v208
	s_addc_u32 s59, s49, 0
	v_add_u32_e32 v133, s65, v209
	ds_read_b128 v[168:171], v131
	ds_read_b128 v[172:175], v133
	s_and_b64 s[48:49], vcc, exec
	s_cselect_b32 s59, s19, s59
	s_cselect_b32 s58, s18, s58
	s_add_u32 s60, s85, s56
	s_addc_u32 s61, s89, s57
	s_and_b64 s[48:49], vcc, exec
	v_cndmask_b32_e32 v138, v132, v190, vcc
	v_cndmask_b32_e32 v0, v143, v214, vcc
	v_cndmask_b32_e32 v140, v130, v194, vcc
	v_cndmask_b32_e32 v188, v142, v192, vcc
	s_cselect_b32 s61, s13, s61
	s_cselect_b32 s60, s12, s60
	s_cselect_b32 s91, 0, s45
	s_cselect_b32 s92, s6, s44
	v_lshl_add_u64 v[202:203], v[134:135], 0, s[56:57]
	s_add_i32 m0, s14, 0xc000
	ds_read_b128 v[176:179], v212
	ds_read_b128 v[180:183], v212 offset:2048
	ds_read_b128 v[184:187], v213
	ds_read_b128 v[216:219], v213 offset:2048
	ds_read_b128 v[220:223], v212 offset:4096
	ds_read_b128 v[224:227], v212 offset:6144
	ds_read_b128 v[230:233], v213 offset:4096
	ds_read_b128 v[234:237], v213 offset:6144
	global_load_lds_dwordx4 v[202:203], off
	v_lshl_add_u64 v[202:203], v[136:137], 0, s[56:57]
	s_add_i32 m0, s14, 0xe000
	s_nop 0
	global_load_lds_dwordx4 v[202:203], off
	s_waitcnt vmcnt(8)
	s_waitcnt lgkmcnt(0)
	s_barrier
	s_setprio 3
	s_waitcnt lgkmcnt(0)
	v_mfma_f32_16x16x32_bf16 v[126:129], v[144:147], v[176:179], v[126:129]
	v_mfma_f32_16x16x32_bf16 v[126:129], v[148:151], v[184:187], v[126:129]
	v_mfma_f32_16x16x32_bf16 v[122:125], v[156:159], v[184:187], v[122:125]
	v_mfma_f32_16x16x32_bf16 v[122:125], v[152:155], v[176:179], v[122:125]
	v_mfma_f32_16x16x32_bf16 v[106:109], v[152:155], v[180:183], v[106:109]
	v_mfma_f32_16x16x32_bf16 v[106:109], v[156:159], v[216:219], v[106:109]
	v_mfma_f32_16x16x32_bf16 v[110:113], v[148:151], v[216:219], v[110:113]
	v_mfma_f32_16x16x32_bf16 v[110:113], v[144:147], v[180:183], v[110:113]
	v_mfma_f32_16x16x32_bf16 v[94:97], v[144:147], v[220:223], v[94:97]
	v_mfma_f32_16x16x32_bf16 v[94:97], v[148:151], v[230:233], v[94:97]
	v_mfma_f32_16x16x32_bf16 v[90:93], v[156:159], v[230:233], v[90:93]
	v_mfma_f32_16x16x32_bf16 v[90:93], v[152:155], v[220:223], v[90:93]
	v_mfma_f32_16x16x32_bf16 v[74:77], v[152:155], v[224:227], v[74:77]
	v_mfma_f32_16x16x32_bf16 v[74:77], v[156:159], v[234:237], v[74:77]
	v_mfma_f32_16x16x32_bf16 v[78:81], v[148:151], v[234:237], v[78:81]
	v_mfma_f32_16x16x32_bf16 v[78:81], v[144:147], v[224:227], v[78:81]
	s_setprio 0
	s_setprio 3
	v_mfma_f32_16x16x32_bf16 v[118:121], v[160:163], v[176:179], v[118:121]
	v_mfma_f32_16x16x32_bf16 v[118:121], v[164:167], v[184:187], v[118:121]
	v_mfma_f32_16x16x32_bf16 v[114:117], v[172:175], v[184:187], v[114:117]
	v_mfma_f32_16x16x32_bf16 v[114:117], v[168:171], v[176:179], v[114:117]
	v_mfma_f32_16x16x32_bf16 v[98:101], v[168:171], v[180:183], v[98:101]
	v_mfma_f32_16x16x32_bf16 v[98:101], v[172:175], v[216:219], v[98:101]
	v_mfma_f32_16x16x32_bf16 v[102:105], v[164:167], v[216:219], v[102:105]
	v_mfma_f32_16x16x32_bf16 v[102:105], v[160:163], v[180:183], v[102:105]
	v_mfma_f32_16x16x32_bf16 v[86:89], v[160:163], v[220:223], v[86:89]
	v_mfma_f32_16x16x32_bf16 v[86:89], v[164:167], v[230:233], v[86:89]
	v_mfma_f32_16x16x32_bf16 v[82:85], v[172:175], v[230:233], v[82:85]
	v_mfma_f32_16x16x32_bf16 v[82:85], v[168:171], v[220:223], v[82:85]
	v_mfma_f32_16x16x32_bf16 v[66:69], v[168:171], v[224:227], v[66:69]
	v_mfma_f32_16x16x32_bf16 v[66:69], v[172:175], v[234:237], v[66:69]
	v_mfma_f32_16x16x32_bf16 v[70:73], v[164:167], v[234:237], v[70:73]
	v_mfma_f32_16x16x32_bf16 v[70:73], v[160:163], v[224:227], v[70:73]
	s_setprio 0
	s_barrier
; #define PG8_STAGE(bufoff, gbase, voff) do { _Pragma("unroll") for (int _i = 0; _i < 2; ++_i) \
;         __builtin_amdgcn_global_load_lds((const unsigned*)((const char*)(gbase) + (voff)[_i]), (LAS unsigned*)(lds + (bufoff) + ldsw + _i * 8192), 16, 0, 0); } while (0)
; #define PG8_LDA(dst, b, h) do { _Pragma("unroll") for (int m = 0; m < 4; ++m) _Pragma("unroll") for (int k = 0; k < 2; ++k) dst[m][k] = *(const LAS bf16x8*)(lds + PG8_SA(b, h) + aoffk[k] + m * 2048); } while (0)
; #define PG8_LDB(dst, b, h) do { _Pragma("unroll") for (int n = 0; n < 2; ++n) _Pragma("unroll") for (int k = 0; k < 2; ++k) dst[n][k] = *(const LAS bf16x8*)(lds + PG8_SB(b, h) + boffk[k] + n * 2048); } while (0)
; #define PG8_WAIT_V(n) asm volatile("s_waitcnt vmcnt(" #n ")" ::: "memory")
; #define PG8_WAIT_L(n) asm volatile("s_waitcnt lgkmcnt(" #n ")" ::: "memory")
; #define PG8_BAR __builtin_amdgcn_s_barrier()
; #define PG8_SCHED __builtin_amdgcn_sched_barrier(0)
; template <class Epi, class Sched, class GemmT>
; __device__ __forceinline__ void gemm_phase(LAS unsigned char* lds, const GemmT& g, const Sched& S, const Epi& E, const int wid) {
;     ...
;                 PG8_WAIT_V(8); PG8_WAIT_L(0); PG8_BAR; PG8_MMA(0, 0, At, B0); PG8_MMA(0, 1, At, B1); PG8_BAR; PG8_SCHED;
;                 PG8_LDA(At, 0, 1); PG8_STAGE(PG8_SB(0, 0), b2, vB2); PG8_STAGE(PG8_SB(0, 1), b2 + hB2, vB2); PG8_STAGE(PG8_SA(0, 0), a2, vA2);
;                 PG8_WAIT_V(8); PG8_WAIT_L(0); PG8_BAR; PG8_MMA(1, 0, At, B0); PG8_MMA(1, 1, At, B1); PG8_BAR; PG8_SCHED;
;                 PG8_LDB(B0, 1, 0); PG8_LDB(B1, 1, 1); PG8_SCHED; PG8_LDA(At, 1, 0); PG8_STAGE(PG8_SA(0, 1), a2 + hA2, vA2);
	s_add_i32 s48, s62, s68
	s_mov_b32 m0, s48
	ds_read_b128 v[176:179], v212 offset:16384
	ds_read_b128 v[180:183], v213 offset:16384
	ds_read_b128 v[184:187], v212 offset:18432
	ds_read_b128 v[216:219], v213 offset:18432
	ds_read_b128 v[220:223], v212 offset:20480
	ds_read_b128 v[224:227], v213 offset:20480
	ds_read_b128 v[230:233], v212 offset:22528
	ds_read_b128 v[234:237], v213 offset:22528
	global_load_lds_dwordx4 v0, s[60:61]
	s_add_i32 m0, s48, 0x2000
	v_mov_b32_e32 v189, v1
	s_add_u32 s48, s60, s92
	v_lshl_add_u64 v[202:203], s[60:61], 0, v[0:1]
	v_lshl_add_u64 v[238:239], s[60:61], 0, v[188:189]
	global_load_lds_dwordx4 v188, s[60:61]
	s_addc_u32 s49, s61, s91
	s_add_i32 s60, s64, s68
	s_mov_b32 m0, s60
	v_mov_b32_e32 v139, v1
	global_load_lds_dwordx4 v0, s[48:49]
	s_add_i32 m0, s60, 0x2000
	v_mov_b32_e32 v141, v1
	global_load_lds_dwordx4 v188, s[48:49]
	s_mov_b32 m0, s14
	v_lshl_add_u64 v[240:241], s[48:49], 0, v[0:1]
	global_load_lds_dwordx4 v138, s[58:59]
	s_mov_b32 m0, s15
	v_lshl_add_u64 v[242:243], s[48:49], 0, v[188:189]
	global_load_lds_dwordx4 v140, s[58:59]
	s_waitcnt vmcnt(8)
	s_waitcnt lgkmcnt(0)
	v_lshl_add_u64 v[188:189], s[58:59], 0, v[138:139]
	v_lshl_add_u64 v[244:245], s[58:59], 0, v[140:141]
	s_barrier
	s_setprio 3
	s_waitcnt lgkmcnt(0)
	v_mfma_f32_16x16x32_bf16 v[62:65], v[144:147], v[176:179], v[62:65]
	v_mfma_f32_16x16x32_bf16 v[62:65], v[148:151], v[180:183], v[62:65]
	v_mfma_f32_16x16x32_bf16 v[58:61], v[156:159], v[180:183], v[58:61]
	v_mfma_f32_16x16x32_bf16 v[58:61], v[152:155], v[176:179], v[58:61]
	v_mfma_f32_16x16x32_bf16 v[42:45], v[152:155], v[184:187], v[42:45]
	v_mfma_f32_16x16x32_bf16 v[42:45], v[156:159], v[216:219], v[42:45]
	v_mfma_f32_16x16x32_bf16 v[46:49], v[148:151], v[216:219], v[46:49]
	v_mfma_f32_16x16x32_bf16 v[46:49], v[144:147], v[184:187], v[46:49]
	v_mfma_f32_16x16x32_bf16 v[30:33], v[144:147], v[220:223], v[30:33]
	v_mfma_f32_16x16x32_bf16 v[30:33], v[148:151], v[224:227], v[30:33]
	v_mfma_f32_16x16x32_bf16 v[22:25], v[156:159], v[224:227], v[22:25]
	v_mfma_f32_16x16x32_bf16 v[22:25], v[152:155], v[220:223], v[22:25]
	v_mfma_f32_16x16x32_bf16 v[6:9], v[152:155], v[230:233], v[6:9]
	v_mfma_f32_16x16x32_bf16 v[6:9], v[156:159], v[234:237], v[6:9]
	v_mfma_f32_16x16x32_bf16 v[14:17], v[148:151], v[234:237], v[14:17]
	v_mfma_f32_16x16x32_bf16 v[14:17], v[144:147], v[230:233], v[14:17]
	s_setprio 0
	s_setprio 3
	v_mfma_f32_16x16x32_bf16 v[54:57], v[160:163], v[176:179], v[54:57]
	v_mfma_f32_16x16x32_bf16 v[54:57], v[164:167], v[180:183], v[54:57]
	v_mfma_f32_16x16x32_bf16 v[50:53], v[172:175], v[180:183], v[50:53]
	v_mfma_f32_16x16x32_bf16 v[50:53], v[168:171], v[176:179], v[50:53]
	v_mfma_f32_16x16x32_bf16 v[34:37], v[168:171], v[184:187], v[34:37]
	v_mfma_f32_16x16x32_bf16 v[34:37], v[172:175], v[216:219], v[34:37]
	v_mfma_f32_16x16x32_bf16 v[38:41], v[164:167], v[216:219], v[38:41]
	v_mfma_f32_16x16x32_bf16 v[38:41], v[160:163], v[184:187], v[38:41]
	v_mfma_f32_16x16x32_bf16 v[26:29], v[160:163], v[220:223], v[26:29]
	v_mfma_f32_16x16x32_bf16 v[26:29], v[164:167], v[224:227], v[26:29]
	v_mfma_f32_16x16x32_bf16 v[18:21], v[172:175], v[224:227], v[18:21]
	v_mfma_f32_16x16x32_bf16 v[18:21], v[168:171], v[220:223], v[18:21]
	v_mfma_f32_16x16x32_bf16 v[2:5], v[168:171], v[230:233], v[2:5]
	v_mfma_f32_16x16x32_bf16 v[2:5], v[172:175], v[234:237], v[2:5]
	v_mfma_f32_16x16x32_bf16 v[10:13], v[164:167], v[234:237], v[10:13]
	v_mfma_f32_16x16x32_bf16 v[10:13], v[160:163], v[230:233], v[10:13]
	s_setprio 0
	s_barrier
	s_add_i32 s60, 0, 0x18000
	v_add_u32_e32 v0, s60, v208
	v_add_u32_e32 v131, s60, v209
	ds_read_b128 v[144:147], v0
	ds_read_b128 v[148:151], v131
	v_add_u32_e32 v0, s66, v208
	s_add_i32 s61, 0, 0x1c000
	v_add_u32_e32 v131, s66, v209
	ds_read_b128 v[152:155], v0
	ds_read_b128 v[156:159], v131
	v_add_u32_e32 v0, s61, v208
	v_add_u32_e32 v131, s61, v209
	ds_read_b128 v[160:163], v0
	ds_read_b128 v[164:167], v131
	v_add_u32_e32 v0, s67, v208
	v_add_u32_e32 v131, s67, v209
	ds_read_b128 v[168:171], v0
	ds_read_b128 v[172:175], v131
	s_add_u32 s48, s58, s92
	s_addc_u32 s49, s59, s91
	s_mov_b32 m0, s34
	ds_read_b128 v[176:179], v212 offset:32768
	ds_read_b128 v[180:183], v212 offset:34816
	ds_read_b128 v[184:187], v213 offset:32768
	ds_read_b128 v[216:219], v213 offset:34816
	ds_read_b128 v[220:223], v212 offset:36864
	ds_read_b128 v[224:227], v212 offset:38912
	ds_read_b128 v[230:233], v213 offset:36864
	ds_read_b128 v[234:237], v213 offset:38912
	global_load_lds_dwordx4 v138, s[48:49]
	s_mov_b32 m0, s35
	s_nop 0
	global_load_lds_dwordx4 v140, s[48:49]
	s_waitcnt vmcnt(8)
	s_waitcnt lgkmcnt(0)
	s_barrier
; #define PG8_STAGE(bufoff, gbase, voff) do { _Pragma("unroll") for (int _i = 0; _i < 2; ++_i) \
;         __builtin_amdgcn_global_load_lds((const unsigned*)((const char*)(gbase) + (voff)[_i]), (LAS unsigned*)(lds + (bufoff) + ldsw + _i * 8192), 16, 0, 0); } while (0)
; #define PG8_LDA(dst, b, h) do { _Pragma("unroll") for (int m = 0; m < 4; ++m) _Pragma("unroll") for (int k = 0; k < 2; ++k) dst[m][k] = *(const LAS bf16x8*)(lds + PG8_SA(b, h) + aoffk[k] + m * 2048); } while (0)
; #define PG8_WAIT_V(n) asm volatile("s_waitcnt vmcnt(" #n ")" ::: "memory")
; #define PG8_WAIT_L(n) asm volatile("s_waitcnt lgkmcnt(" #n ")" ::: "memory")
; #define PG8_BAR __builtin_amdgcn_s_barrier()
; #define PG8_SCHED __builtin_amdgcn_sched_barrier(0)
; template <class Epi, class Sched, class GemmT>
; __device__ __forceinline__ void gemm_phase(LAS unsigned char* lds, const GemmT& g, const Sched& S, const Epi& E, const int wid) {
;     ...
;                 PG8_WAIT_V(8); PG8_WAIT_L(0); PG8_BAR; PG8_MMA(0, 0, At, B0); PG8_MMA(0, 1, At, B1); PG8_BAR; PG8_SCHED;
;                 PG8_LDA(At, 1, 1); PG8_STAGE(PG8_SB(1, 0), b3, vB2); PG8_STAGE(PG8_SB(1, 1), b3 + hB2, vB2); PG8_STAGE(PG8_SA(1, 0), a3, vA2);
;                 PG8_WAIT_V(8); PG8_WAIT_L(0); PG8_BAR; PG8_MMA(1, 0, At, B0); PG8_MMA(1, 1, At, B1); PG8_BAR; PG8_SCHED;
	s_setprio 3
	s_waitcnt lgkmcnt(0)
	v_mfma_f32_16x16x32_bf16 v[126:129], v[144:147], v[176:179], v[126:129]
	v_mfma_f32_16x16x32_bf16 v[126:129], v[148:151], v[184:187], v[126:129]
	v_mfma_f32_16x16x32_bf16 v[122:125], v[156:159], v[184:187], v[122:125]
	v_mfma_f32_16x16x32_bf16 v[122:125], v[152:155], v[176:179], v[122:125]
	v_mfma_f32_16x16x32_bf16 v[106:109], v[152:155], v[180:183], v[106:109]
	v_mfma_f32_16x16x32_bf16 v[106:109], v[156:159], v[216:219], v[106:109]
	v_mfma_f32_16x16x32_bf16 v[110:113], v[148:151], v[216:219], v[110:113]
	v_mfma_f32_16x16x32_bf16 v[110:113], v[144:147], v[180:183], v[110:113]
	v_mfma_f32_16x16x32_bf16 v[94:97], v[144:147], v[220:223], v[94:97]
	v_mfma_f32_16x16x32_bf16 v[94:97], v[148:151], v[230:233], v[94:97]
	v_mfma_f32_16x16x32_bf16 v[90:93], v[156:159], v[230:233], v[90:93]
	v_mfma_f32_16x16x32_bf16 v[90:93], v[152:155], v[220:223], v[90:93]
	v_mfma_f32_16x16x32_bf16 v[74:77], v[152:155], v[224:227], v[74:77]
	v_mfma_f32_16x16x32_bf16 v[74:77], v[156:159], v[234:237], v[74:77]
	v_mfma_f32_16x16x32_bf16 v[78:81], v[148:151], v[234:237], v[78:81]
	v_mfma_f32_16x16x32_bf16 v[78:81], v[144:147], v[224:227], v[78:81]
	s_setprio 0
	s_setprio 3
	v_mfma_f32_16x16x32_bf16 v[118:121], v[160:163], v[176:179], v[118:121]
	v_mfma_f32_16x16x32_bf16 v[118:121], v[164:167], v[184:187], v[118:121]
	v_mfma_f32_16x16x32_bf16 v[114:117], v[172:175], v[184:187], v[114:117]
	v_mfma_f32_16x16x32_bf16 v[114:117], v[168:171], v[176:179], v[114:117]
	v_mfma_f32_16x16x32_bf16 v[98:101], v[168:171], v[180:183], v[98:101]
	v_mfma_f32_16x16x32_bf16 v[98:101], v[172:175], v[216:219], v[98:101]
	v_mfma_f32_16x16x32_bf16 v[102:105], v[164:167], v[216:219], v[102:105]
	v_mfma_f32_16x16x32_bf16 v[102:105], v[160:163], v[180:183], v[102:105]
	v_mfma_f32_16x16x32_bf16 v[86:89], v[160:163], v[220:223], v[86:89]
	v_mfma_f32_16x16x32_bf16 v[86:89], v[164:167], v[230:233], v[86:89]
	v_mfma_f32_16x16x32_bf16 v[82:85], v[172:175], v[230:233], v[82:85]
	v_mfma_f32_16x16x32_bf16 v[82:85], v[168:171], v[220:223], v[82:85]
	v_mfma_f32_16x16x32_bf16 v[66:69], v[168:171], v[224:227], v[66:69]
	v_mfma_f32_16x16x32_bf16 v[66:69], v[172:175], v[234:237], v[66:69]
	v_mfma_f32_16x16x32_bf16 v[70:73], v[164:167], v[234:237], v[70:73]
	v_mfma_f32_16x16x32_bf16 v[70:73], v[160:163], v[224:227], v[70:73]
	s_setprio 0
	s_barrier
	s_add_i32 s48, s60, s68
	v_lshl_add_u64 v[202:203], v[202:203], 0, s[20:21]
	s_mov_b32 m0, s48
	ds_read_b128 v[138:141], v212 offset:49152
	ds_read_b128 v[176:179], v212 offset:51200
	ds_read_b128 v[180:183], v213 offset:49152
	ds_read_b128 v[184:187], v213 offset:51200
	ds_read_b128 v[216:219], v212 offset:53248
	ds_read_b128 v[220:223], v212 offset:55296
	ds_read_b128 v[224:227], v213 offset:53248
	ds_read_b128 v[230:233], v213 offset:55296
	global_load_lds_dwordx4 v[202:203], off
	v_lshl_add_u64 v[202:203], v[238:239], 0, s[20:21]
	s_add_i32 m0, s48, 0x2000
	s_add_i32 s48, s61, s68
	global_load_lds_dwordx4 v[202:203], off
	v_lshl_add_u64 v[202:203], v[240:241], 0, s[20:21]
	s_mov_b32 m0, s48
	v_lshl_add_u64 v[188:189], v[188:189], 0, s[20:21]
	global_load_lds_dwordx4 v[202:203], off
	v_lshl_add_u64 v[202:203], v[242:243], 0, s[20:21]
	s_add_i32 m0, s48, 0x2000
	s_nop 0
	global_load_lds_dwordx4 v[202:203], off
	s_mov_b32 m0, s54
	s_nop 0
	global_load_lds_dwordx4 v[188:189], off
	v_lshl_add_u64 v[188:189], v[244:245], 0, s[20:21]
	s_mov_b32 m0, s55
	s_nop 0
	global_load_lds_dwordx4 v[188:189], off
	s_waitcnt vmcnt(8)
	s_waitcnt lgkmcnt(0)
	s_barrier
	s_setprio 3
	s_waitcnt lgkmcnt(0)
	v_mfma_f32_16x16x32_bf16 v[62:65], v[144:147], v[138:141], v[62:65]
	v_mfma_f32_16x16x32_bf16 v[62:65], v[148:151], v[180:183], v[62:65]
	v_mfma_f32_16x16x32_bf16 v[58:61], v[156:159], v[180:183], v[58:61]
	v_mfma_f32_16x16x32_bf16 v[58:61], v[152:155], v[138:141], v[58:61]
	v_mfma_f32_16x16x32_bf16 v[42:45], v[152:155], v[176:179], v[42:45]
	v_mfma_f32_16x16x32_bf16 v[42:45], v[156:159], v[184:187], v[42:45]
	v_mfma_f32_16x16x32_bf16 v[46:49], v[148:151], v[184:187], v[46:49]
	v_mfma_f32_16x16x32_bf16 v[46:49], v[144:147], v[176:179], v[46:49]
	v_mfma_f32_16x16x32_bf16 v[30:33], v[144:147], v[216:219], v[30:33]
	v_mfma_f32_16x16x32_bf16 v[30:33], v[148:151], v[224:227], v[30:33]
	v_mfma_f32_16x16x32_bf16 v[22:25], v[156:159], v[224:227], v[22:25]
	v_mfma_f32_16x16x32_bf16 v[22:25], v[152:155], v[216:219], v[22:25]
	v_mfma_f32_16x16x32_bf16 v[6:9], v[152:155], v[220:223], v[6:9]
	v_mfma_f32_16x16x32_bf16 v[6:9], v[156:159], v[230:233], v[6:9]
	v_mfma_f32_16x16x32_bf16 v[14:17], v[148:151], v[230:233], v[14:17]
	v_mfma_f32_16x16x32_bf16 v[14:17], v[144:147], v[220:223], v[14:17]
	s_setprio 0
	s_setprio 3
	v_mfma_f32_16x16x32_bf16 v[54:57], v[160:163], v[138:141], v[54:57]
	v_mfma_f32_16x16x32_bf16 v[54:57], v[164:167], v[180:183], v[54:57]
	v_mfma_f32_16x16x32_bf16 v[50:53], v[172:175], v[180:183], v[50:53]
	v_mfma_f32_16x16x32_bf16 v[50:53], v[168:171], v[138:141], v[50:53]
	v_mfma_f32_16x16x32_bf16 v[34:37], v[168:171], v[176:179], v[34:37]
	v_mfma_f32_16x16x32_bf16 v[34:37], v[172:175], v[184:187], v[34:37]
	v_mfma_f32_16x16x32_bf16 v[38:41], v[164:167], v[184:187], v[38:41]
	v_mfma_f32_16x16x32_bf16 v[38:41], v[160:163], v[176:179], v[38:41]
	v_mfma_f32_16x16x32_bf16 v[26:29], v[160:163], v[216:219], v[26:29]
	v_mfma_f32_16x16x32_bf16 v[26:29], v[164:167], v[224:227], v[26:29]
	v_mfma_f32_16x16x32_bf16 v[18:21], v[172:175], v[224:227], v[18:21]
	v_mfma_f32_16x16x32_bf16 v[18:21], v[168:171], v[216:219], v[18:21]
	v_mfma_f32_16x16x32_bf16 v[2:5], v[168:171], v[220:223], v[2:5]
	v_mfma_f32_16x16x32_bf16 v[2:5], v[172:175], v[230:233], v[2:5]
	v_mfma_f32_16x16x32_bf16 v[10:13], v[164:167], v[230:233], v[10:13]
	v_mfma_f32_16x16x32_bf16 v[10:13], v[160:163], v[220:223], v[10:13]
	s_setprio 0
	s_barrier
; #define PG8_WAIT_V(n) asm volatile("s_waitcnt vmcnt(" #n ")" ::: "memory")
; #define PG8_WAIT_L(n) asm volatile("s_waitcnt lgkmcnt(" #n ")" ::: "memory")
; #define PG8_BAR __builtin_amdgcn_s_barrier()
; #define PG8_SCHED __builtin_amdgcn_sched_barrier(0)
;     __device__ __forceinline__ void mid(Acc& acc, const Unit& u, int s, int wr, int wc, int fr, int fq) const {
;         int lo = (wr * 4 + wc) * 8192 + (fq * 16 + fr) * 16; asm volatile("" : "+v"(lo));
;         const unsigned char* gp = gate + ((size_t)(u.pm * 48 + s * 16 + u.pn) << 16) + lo;
;         u32x4 G[8][2];
; #pragma unroll
;         for (int i = 0; i < 8; ++i) { G[i][0] = __builtin_nontemporal_load((const u32x4*)(gp + i * 1024)); G[i][1] = __builtin_nontemporal_load((const u32x4*)(gp + (1 << 20) + i * 1024)); }
; #pragma unroll
;         for (int i = 0; i < 8; ++i) { const int ai = i >> 2, m = i & 3;
; #pragma unroll
;             for (int bj = 0; bj < 2; ++bj) {
;                 const u32x4 ga = G[i][0], gb = G[i][1];
;                 const u32x2 wa = bj == 0 ? (u32x2){ga.x, ga.y} : (u32x2){ga.z, ga.w}, wb = bj == 0 ? (u32x2){gb.x, gb.y} : (u32x2){gb.z, gb.w};
;                 float fa[8], fb[8]; gate_unpack8(wa, fa); gate_unpack8(wb, fb);
; #pragma unroll
;                 for (int e = 0; e < 8; ++e) fa[e] = fa[e] * __builtin_amdgcn_rcpf(fb[e]);
;                 f32x4& v0 = acc[ai][bj][m][0]; f32x4& v1 = acc[ai][bj][m][1];
;                 v0[0] *= fa[0]; v0[1] *= fa[1]; v0[2] *= fa[2]; v0[3] *= fa[3]; v1[0] *= fa[4]; v1[1] *= fa[5]; v1[2] *= fa[6]; v1[3] *= fa[7]; }
; template <class Epi, class Sched, class GemmT>
; __device__ __forceinline__ void gemm_phase(LAS unsigned char* lds, const GemmT& g, const Sched& S, const Epi& E, const int wid) {
;     ...
;                 PG8_WAIT_V(8); PG8_WAIT_L(0); PG8_BAR; PG8_MMA(1, 0, At, B0); PG8_MMA(1, 1, At, B1); PG8_BAR; PG8_SCHED;
;             }
;             if constexpr (NSEG > 1) { if (sgi + 1 < NSEG) E.mid(acc, cur, sgi, wr, wc, fr, fq); }
	s_add_u32 s56, s56, 0x100
	s_addc_u32 s57, s57, 0
	s_cmp_ge_u32 s90, s42
	s_cbranch_scc0 .LBB0_764
	s_nop 0
	s_and_b64 vcc, exec, s[52:53]
	s_cbranch_vccz .LBB0_767
	s_lshl_b32 s42, s83, 4
	s_add_i32 s42, s82, s42
	s_ashr_i32 s43, s42, 31
	s_lshl_b64 s[42:43], s[42:43], 16
	v_mov_b32_e32 v130, v210
	s_add_u32 s42, s22, s42
	s_addc_u32 s43, s23, s43
	v_ashrrev_i32_e32 v131, 31, v130
	v_lshl_add_u64 v[130:131], s[42:43], 0, v[130:131]
	v_add_co_u32_e32 v132, vcc, s69, v130
	s_mov_b32 s42, 0x101000
	s_nop 0
	v_addc_co_u32_e32 v133, vcc, 0, v131, vcc
	global_load_dwordx4 v[186:189], v[130:131], off nt
	v_add_co_u32_e32 v134, vcc, s42, v130
	s_movk_i32 s42, 0x1000
	s_nop 0
	v_addc_co_u32_e32 v135, vcc, 0, v131, vcc
	global_load_dwordx4 v[216:219], v[134:135], off offset:-4096 nt
	global_load_dwordx4 v[178:181], v[130:131], off offset:1024 nt
	global_load_dwordx4 v[182:185], v[132:133], off offset:1024 nt
	global_load_dwordx4 v[170:173], v[130:131], off offset:2048 nt
	global_load_dwordx4 v[174:177], v[132:133], off offset:2048 nt
	global_load_dwordx4 v[162:165], v[130:131], off offset:3072 nt
	global_load_dwordx4 v[166:169], v[132:133], off offset:3072 nt
	v_add_co_u32_e32 v130, vcc, s42, v130
	s_waitcnt vmcnt(0)
	v_cvt_f32_ubyte0_e32 v0, v216
	v_addc_co_u32_e32 v131, vcc, 0, v131, vcc
	global_load_dwordx4 v[154:157], v[130:131], off nt
	global_load_dwordx4 v[158:161], v[134:135], off nt
	global_load_dwordx4 v[146:149], v[130:131], off offset:1024 nt
	global_load_dwordx4 v[150:153], v[134:135], off offset:1024 nt
	global_load_dwordx4 v[138:141], v[130:131], off offset:2048 nt
	global_load_dwordx4 v[142:145], v[134:135], off offset:2048 nt
	s_nop 0
	global_load_dwordx4 v[130:133], v[130:131], off offset:3072 nt
	s_nop 0
	global_load_dwordx4 v[134:137], v[134:135], off offset:3072 nt
	v_cvt_f32_ubyte1_e32 v203, v216
	v_cvt_f32_ubyte2_e32 v215, v216
	v_cvt_f32_ubyte3_e32 v220, v216
	v_cvt_f32_ubyte0_e32 v221, v217
	v_cvt_f32_ubyte1_e32 v222, v217
	v_cvt_f32_ubyte2_e32 v223, v217
	v_cvt_f32_ubyte3_e32 v224, v217
	v_rcp_iflag_f32_e32 v202, v0
	v_rcp_iflag_f32_e32 v203, v203
	v_rcp_iflag_f32_e32 v216, v215
	v_rcp_iflag_f32_e32 v217, v220
	v_rcp_iflag_f32_e32 v220, v221
	v_rcp_iflag_f32_e32 v221, v222
	v_rcp_iflag_f32_e32 v222, v223
	v_rcp_iflag_f32_e32 v223, v224
	v_cvt_f32_ubyte3_e32 v225, v186
	v_cvt_f32_ubyte2_e32 v224, v186
	v_cvt_f32_ubyte1_e32 v227, v186
	v_cvt_f32_ubyte0_e32 v226, v186
	v_pk_mul_f32 v[202:203], v[202:203], v[226:227]
	v_pk_mul_f32 v[216:217], v[216:217], v[224:225]
	v_pk_mul_f32 v[126:127], v[126:127], v[202:203]
	v_pk_mul_f32 v[128:129], v[128:129], v[216:217]
	v_cvt_f32_ubyte3_e32 v203, v187
	v_cvt_f32_ubyte2_e32 v202, v187
	v_cvt_f32_ubyte1_e32 v217, v187
	v_cvt_f32_ubyte0_e32 v216, v187
	v_pk_mul_f32 v[186:187], v[220:221], v[216:217]
	v_pk_mul_f32 v[202:203], v[222:223], v[202:203]
	v_pk_mul_f32 v[122:123], v[122:123], v[186:187]
	v_pk_mul_f32 v[124:125], v[124:125], v[202:203]
	v_cvt_f32_ubyte0_e32 v0, v218
	v_cvt_f32_ubyte1_e32 v186, v218
	v_cvt_f32_ubyte2_e32 v187, v218
	v_cvt_f32_ubyte3_e32 v202, v218
	v_cvt_f32_ubyte0_e32 v203, v219
	v_cvt_f32_ubyte1_e32 v215, v219
	v_cvt_f32_ubyte2_e32 v220, v219
	v_cvt_f32_ubyte3_e32 v221, v219
	v_rcp_iflag_f32_e32 v216, v0
	v_rcp_iflag_f32_e32 v217, v186
	v_rcp_iflag_f32_e32 v218, v187
	v_rcp_iflag_f32_e32 v219, v202
	v_rcp_iflag_f32_e32 v202, v203
	v_rcp_iflag_f32_e32 v203, v215
	v_rcp_iflag_f32_e32 v186, v220
	v_rcp_iflag_f32_e32 v187, v221
	v_cvt_f32_ubyte3_e32 v221, v188
	v_cvt_f32_ubyte2_e32 v220, v188
	v_cvt_f32_ubyte1_e32 v223, v188
	v_cvt_f32_ubyte0_e32 v222, v188
	v_pk_mul_f32 v[216:217], v[216:217], v[222:223]
	v_pk_mul_f32 v[218:219], v[218:219], v[220:221]
	v_pk_mul_f32 v[118:119], v[118:119], v[216:217]
	v_pk_mul_f32 v[120:121], v[120:121], v[218:219]
	v_cvt_f32_ubyte3_e32 v217, v189
	v_cvt_f32_ubyte2_e32 v216, v189
	v_cvt_f32_ubyte1_e32 v219, v189
	v_cvt_f32_ubyte0_e32 v218, v189
	v_pk_mul_f32 v[188:189], v[202:203], v[218:219]
	v_pk_mul_f32 v[186:187], v[186:187], v[216:217]
	v_pk_mul_f32 v[114:115], v[114:115], v[188:189]
	v_pk_mul_f32 v[116:117], v[116:117], v[186:187]
	v_cvt_f32_ubyte0_e32 v0, v182
	v_cvt_f32_ubyte1_e32 v186, v182
	v_cvt_f32_ubyte2_e32 v187, v182
	v_cvt_f32_ubyte3_e32 v188, v182
	v_cvt_f32_ubyte0_e32 v189, v183
	v_cvt_f32_ubyte1_e32 v202, v183
	v_cvt_f32_ubyte2_e32 v203, v183
	v_cvt_f32_ubyte3_e32 v215, v183
	v_rcp_iflag_f32_e32 v182, v0
	v_rcp_iflag_f32_e32 v183, v186
	v_rcp_iflag_f32_e32 v186, v187
	v_rcp_iflag_f32_e32 v187, v188
	v_rcp_iflag_f32_e32 v188, v189
	v_rcp_iflag_f32_e32 v189, v202
	v_rcp_iflag_f32_e32 v202, v203
	v_rcp_iflag_f32_e32 v203, v215
	v_cvt_f32_ubyte3_e32 v217, v178
	v_cvt_f32_ubyte2_e32 v216, v178
	v_cvt_f32_ubyte1_e32 v219, v178
	v_cvt_f32_ubyte0_e32 v218, v178
	v_pk_mul_f32 v[182:183], v[182:183], v[218:219]
	v_pk_mul_f32 v[186:187], v[186:187], v[216:217]
	v_pk_mul_f32 v[110:111], v[110:111], v[182:183]
	v_pk_mul_f32 v[112:113], v[112:113], v[186:187]
	v_cvt_f32_ubyte3_e32 v183, v179
	v_cvt_f32_ubyte2_e32 v182, v179
	v_cvt_f32_ubyte1_e32 v187, v179
	v_cvt_f32_ubyte0_e32 v186, v179
	v_pk_mul_f32 v[178:179], v[188:189], v[186:187]
	v_pk_mul_f32 v[182:183], v[202:203], v[182:183]
	v_pk_mul_f32 v[106:107], v[106:107], v[178:179]
	v_pk_mul_f32 v[108:109], v[108:109], v[182:183]
	v_cvt_f32_ubyte0_e32 v0, v184
	v_cvt_f32_ubyte1_e32 v179, v184
	v_cvt_f32_ubyte2_e32 v182, v184
	v_cvt_f32_ubyte3_e32 v183, v184
	v_rcp_iflag_f32_e32 v178, v0
	v_rcp_iflag_f32_e32 v179, v179
	v_rcp_iflag_f32_e32 v182, v182
	v_rcp_iflag_f32_e32 v183, v183
	v_cvt_f32_ubyte0_e32 v184, v185
	v_cvt_f32_ubyte1_e32 v186, v185
	v_cvt_f32_ubyte2_e32 v187, v185
;     __device__ __forceinline__ void mid(Acc& acc, const Unit& u, int s, int wr, int wc, int fr, int fq) const {
;     ...
;         for (int i = 0; i < 8; ++i) { const int ai = i >> 2, m = i & 3;
; #pragma unroll
;             for (int bj = 0; bj < 2; ++bj) {
;                 const u32x4 ga = G[i][0], gb = G[i][1];
;                 const u32x2 wa = bj == 0 ? (u32x2){ga.x, ga.y} : (u32x2){ga.z, ga.w}, wb = bj == 0 ? (u32x2){gb.x, gb.y} : (u32x2){gb.z, gb.w};
;                 float fa[8], fb[8]; gate_unpack8(wa, fa); gate_unpack8(wb, fb);
; #pragma unroll
;                 for (int e = 0; e < 8; ++e) fa[e] = fa[e] * __builtin_amdgcn_rcpf(fb[e]);
;                 f32x4& v0 = acc[ai][bj][m][0]; f32x4& v1 = acc[ai][bj][m][1];
;                 v0[0] *= fa[0]; v0[1] *= fa[1]; v0[2] *= fa[2]; v0[3] *= fa[3]; v1[0] *= fa[4]; v1[1] *= fa[5]; v1[2] *= fa[6]; v1[3] *= fa[7]; }
	v_cvt_f32_ubyte3_e32 v188, v185
	v_rcp_iflag_f32_e32 v184, v184
	v_rcp_iflag_f32_e32 v185, v186
	v_rcp_iflag_f32_e32 v186, v187
	v_rcp_iflag_f32_e32 v187, v188
	v_cvt_f32_ubyte3_e32 v189, v180
	v_cvt_f32_ubyte2_e32 v188, v180
	v_cvt_f32_ubyte1_e32 v203, v180
	v_cvt_f32_ubyte0_e32 v202, v180
	v_pk_mul_f32 v[178:179], v[178:179], v[202:203]
	v_pk_mul_f32 v[182:183], v[182:183], v[188:189]
	v_pk_mul_f32 v[102:103], v[102:103], v[178:179]
	v_pk_mul_f32 v[104:105], v[104:105], v[182:183]
	v_cvt_f32_ubyte3_e32 v179, v181
	v_cvt_f32_ubyte2_e32 v178, v181
	v_cvt_f32_ubyte1_e32 v183, v181
	v_cvt_f32_ubyte0_e32 v182, v181
	v_pk_mul_f32 v[180:181], v[184:185], v[182:183]
	v_pk_mul_f32 v[178:179], v[186:187], v[178:179]
	v_pk_mul_f32 v[98:99], v[98:99], v[180:181]
	v_pk_mul_f32 v[100:101], v[100:101], v[178:179]
	v_cvt_f32_ubyte0_e32 v0, v174
	v_cvt_f32_ubyte1_e32 v178, v174
	v_cvt_f32_ubyte2_e32 v179, v174
	v_cvt_f32_ubyte3_e32 v180, v174
	v_cvt_f32_ubyte0_e32 v181, v175
	v_cvt_f32_ubyte1_e32 v182, v175
	v_cvt_f32_ubyte2_e32 v183, v175
	v_cvt_f32_ubyte3_e32 v184, v175
	v_rcp_iflag_f32_e32 v174, v0
	v_rcp_iflag_f32_e32 v175, v178
	v_rcp_iflag_f32_e32 v178, v179
	v_rcp_iflag_f32_e32 v179, v180
	v_rcp_iflag_f32_e32 v180, v181
	v_rcp_iflag_f32_e32 v181, v182
	v_rcp_iflag_f32_e32 v182, v183
	v_rcp_iflag_f32_e32 v183, v184
	v_cvt_f32_ubyte3_e32 v185, v170
	v_cvt_f32_ubyte2_e32 v184, v170
	v_cvt_f32_ubyte1_e32 v187, v170
	v_cvt_f32_ubyte0_e32 v186, v170
	v_pk_mul_f32 v[174:175], v[174:175], v[186:187]
	v_pk_mul_f32 v[178:179], v[178:179], v[184:185]
	v_pk_mul_f32 v[94:95], v[94:95], v[174:175]
	v_pk_mul_f32 v[96:97], v[96:97], v[178:179]
	v_cvt_f32_ubyte3_e32 v175, v171
	v_cvt_f32_ubyte2_e32 v174, v171
	v_cvt_f32_ubyte1_e32 v179, v171
	v_cvt_f32_ubyte0_e32 v178, v171
	v_pk_mul_f32 v[170:171], v[180:181], v[178:179]
	v_pk_mul_f32 v[174:175], v[182:183], v[174:175]
	v_pk_mul_f32 v[90:91], v[90:91], v[170:171]
	v_pk_mul_f32 v[92:93], v[92:93], v[174:175]
	v_cvt_f32_ubyte0_e32 v0, v176
	v_cvt_f32_ubyte1_e32 v171, v176
	v_cvt_f32_ubyte2_e32 v174, v176
	v_cvt_f32_ubyte3_e32 v175, v176
	v_rcp_iflag_f32_e32 v170, v0
	v_rcp_iflag_f32_e32 v171, v171
	v_rcp_iflag_f32_e32 v174, v174
	v_rcp_iflag_f32_e32 v175, v175
	v_cvt_f32_ubyte0_e32 v176, v177
	v_cvt_f32_ubyte1_e32 v178, v177
	v_cvt_f32_ubyte2_e32 v179, v177
	v_cvt_f32_ubyte3_e32 v180, v177
	v_rcp_iflag_f32_e32 v176, v176
	v_rcp_iflag_f32_e32 v177, v178
	v_rcp_iflag_f32_e32 v178, v179
	v_rcp_iflag_f32_e32 v179, v180
	v_cvt_f32_ubyte3_e32 v181, v172
	v_cvt_f32_ubyte2_e32 v180, v172
	v_cvt_f32_ubyte1_e32 v183, v172
	v_cvt_f32_ubyte0_e32 v182, v172
	v_pk_mul_f32 v[170:171], v[170:171], v[182:183]
	v_pk_mul_f32 v[174:175], v[174:175], v[180:181]
	v_pk_mul_f32 v[86:87], v[86:87], v[170:171]
	v_pk_mul_f32 v[88:89], v[88:89], v[174:175]
	v_cvt_f32_ubyte3_e32 v171, v173
	v_cvt_f32_ubyte2_e32 v170, v173
	v_cvt_f32_ubyte1_e32 v175, v173
	v_cvt_f32_ubyte0_e32 v174, v173
	v_pk_mul_f32 v[172:173], v[176:177], v[174:175]
	v_pk_mul_f32 v[170:171], v[178:179], v[170:171]
	v_pk_mul_f32 v[82:83], v[82:83], v[172:173]
	v_pk_mul_f32 v[84:85], v[84:85], v[170:171]
	v_cvt_f32_ubyte0_e32 v0, v166
	v_cvt_f32_ubyte1_e32 v170, v166
	v_cvt_f32_ubyte2_e32 v171, v166
	v_cvt_f32_ubyte3_e32 v172, v166
	v_cvt_f32_ubyte0_e32 v173, v167
	v_cvt_f32_ubyte1_e32 v174, v167
	v_cvt_f32_ubyte2_e32 v175, v167
	v_cvt_f32_ubyte3_e32 v176, v167
	v_rcp_iflag_f32_e32 v166, v0
	v_rcp_iflag_f32_e32 v167, v170
	v_rcp_iflag_f32_e32 v170, v171
	v_rcp_iflag_f32_e32 v171, v172
	v_rcp_iflag_f32_e32 v172, v173
	v_rcp_iflag_f32_e32 v173, v174
	v_rcp_iflag_f32_e32 v174, v175
	v_rcp_iflag_f32_e32 v175, v176
	v_cvt_f32_ubyte3_e32 v177, v162
	v_cvt_f32_ubyte2_e32 v176, v162
	v_cvt_f32_ubyte1_e32 v179, v162
	v_cvt_f32_ubyte0_e32 v178, v162
	v_pk_mul_f32 v[166:167], v[166:167], v[178:179]
	v_pk_mul_f32 v[170:171], v[170:171], v[176:177]
	v_pk_mul_f32 v[78:79], v[78:79], v[166:167]
	v_pk_mul_f32 v[80:81], v[80:81], v[170:171]
	v_cvt_f32_ubyte3_e32 v167, v163
	v_cvt_f32_ubyte2_e32 v166, v163
	v_cvt_f32_ubyte1_e32 v171, v163
	v_cvt_f32_ubyte0_e32 v170, v163
	v_pk_mul_f32 v[162:163], v[172:173], v[170:171]
	v_pk_mul_f32 v[166:167], v[174:175], v[166:167]
	v_pk_mul_f32 v[74:75], v[74:75], v[162:163]
	v_pk_mul_f32 v[76:77], v[76:77], v[166:167]
	v_cvt_f32_ubyte0_e32 v0, v168
	v_cvt_f32_ubyte1_e32 v163, v168
	v_cvt_f32_ubyte2_e32 v166, v168
	v_cvt_f32_ubyte3_e32 v167, v168
	v_rcp_iflag_f32_e32 v162, v0
	v_rcp_iflag_f32_e32 v163, v163
	v_rcp_iflag_f32_e32 v166, v166
	v_rcp_iflag_f32_e32 v167, v167
	v_cvt_f32_ubyte0_e32 v168, v169
	v_cvt_f32_ubyte1_e32 v170, v169
	v_cvt_f32_ubyte2_e32 v171, v169
	v_cvt_f32_ubyte3_e32 v172, v169
	v_rcp_iflag_f32_e32 v168, v168
	v_rcp_iflag_f32_e32 v169, v170
	v_rcp_iflag_f32_e32 v170, v171
	v_rcp_iflag_f32_e32 v171, v172
	v_cvt_f32_ubyte3_e32 v173, v164
	v_cvt_f32_ubyte2_e32 v172, v164
	v_cvt_f32_ubyte1_e32 v175, v164
	v_cvt_f32_ubyte0_e32 v174, v164
	v_pk_mul_f32 v[162:163], v[162:163], v[174:175]
	v_pk_mul_f32 v[166:167], v[166:167], v[172:173]
	v_pk_mul_f32 v[70:71], v[70:71], v[162:163]
	v_pk_mul_f32 v[72:73], v[72:73], v[166:167]
	v_cvt_f32_ubyte3_e32 v163, v165
	v_cvt_f32_ubyte2_e32 v162, v165
	v_cvt_f32_ubyte1_e32 v167, v165
	v_cvt_f32_ubyte0_e32 v166, v165
	v_pk_mul_f32 v[164:165], v[168:169], v[166:167]
	v_pk_mul_f32 v[162:163], v[170:171], v[162:163]
	v_pk_mul_f32 v[66:67], v[66:67], v[164:165]
	v_pk_mul_f32 v[68:69], v[68:69], v[162:163]
	s_waitcnt vmcnt(6)
;     __device__ __forceinline__ void mid(Acc& acc, const Unit& u, int s, int wr, int wc, int fr, int fq) const {
;     ...
;         for (int i = 0; i < 8; ++i) { const int ai = i >> 2, m = i & 3;
; #pragma unroll
;             for (int bj = 0; bj < 2; ++bj) {
;                 const u32x4 ga = G[i][0], gb = G[i][1];
;                 const u32x2 wa = bj == 0 ? (u32x2){ga.x, ga.y} : (u32x2){ga.z, ga.w}, wb = bj == 0 ? (u32x2){gb.x, gb.y} : (u32x2){gb.z, gb.w};
;                 float fa[8], fb[8]; gate_unpack8(wa, fa); gate_unpack8(wb, fb);
; #pragma unroll
;                 for (int e = 0; e < 8; ++e) fa[e] = fa[e] * __builtin_amdgcn_rcpf(fb[e]);
;                 f32x4& v0 = acc[ai][bj][m][0]; f32x4& v1 = acc[ai][bj][m][1];
;                 v0[0] *= fa[0]; v0[1] *= fa[1]; v0[2] *= fa[2]; v0[3] *= fa[3]; v1[0] *= fa[4]; v1[1] *= fa[5]; v1[2] *= fa[6]; v1[3] *= fa[7]; }
	v_cvt_f32_ubyte0_e32 v0, v158
	v_cvt_f32_ubyte1_e32 v162, v158
	v_cvt_f32_ubyte2_e32 v163, v158
	v_cvt_f32_ubyte3_e32 v164, v158
	v_cvt_f32_ubyte0_e32 v165, v159
	v_cvt_f32_ubyte1_e32 v166, v159
	v_cvt_f32_ubyte2_e32 v167, v159
	v_cvt_f32_ubyte3_e32 v168, v159
	v_rcp_iflag_f32_e32 v158, v0
	v_rcp_iflag_f32_e32 v159, v162
	v_rcp_iflag_f32_e32 v162, v163
	v_rcp_iflag_f32_e32 v163, v164
	v_rcp_iflag_f32_e32 v164, v165
	v_rcp_iflag_f32_e32 v165, v166
	v_rcp_iflag_f32_e32 v166, v167
	v_rcp_iflag_f32_e32 v167, v168
	v_cvt_f32_ubyte3_e32 v169, v154
	v_cvt_f32_ubyte2_e32 v168, v154
	v_cvt_f32_ubyte1_e32 v171, v154
	v_cvt_f32_ubyte0_e32 v170, v154
	v_pk_mul_f32 v[158:159], v[158:159], v[170:171]
	v_pk_mul_f32 v[162:163], v[162:163], v[168:169]
	v_pk_mul_f32 v[62:63], v[62:63], v[158:159]
	v_pk_mul_f32 v[64:65], v[64:65], v[162:163]
	v_cvt_f32_ubyte3_e32 v159, v155
	v_cvt_f32_ubyte2_e32 v158, v155
	v_cvt_f32_ubyte1_e32 v163, v155
	v_cvt_f32_ubyte0_e32 v162, v155
	v_pk_mul_f32 v[154:155], v[164:165], v[162:163]
	v_pk_mul_f32 v[158:159], v[166:167], v[158:159]
	v_pk_mul_f32 v[58:59], v[58:59], v[154:155]
	v_pk_mul_f32 v[60:61], v[60:61], v[158:159]
	v_cvt_f32_ubyte0_e32 v0, v160
	v_cvt_f32_ubyte1_e32 v155, v160
	v_cvt_f32_ubyte2_e32 v158, v160
	v_cvt_f32_ubyte3_e32 v159, v160
	v_rcp_iflag_f32_e32 v154, v0
	v_rcp_iflag_f32_e32 v155, v155
	v_rcp_iflag_f32_e32 v158, v158
	v_rcp_iflag_f32_e32 v159, v159
	v_cvt_f32_ubyte0_e32 v160, v161
	v_cvt_f32_ubyte1_e32 v162, v161
	v_cvt_f32_ubyte2_e32 v163, v161
	v_cvt_f32_ubyte3_e32 v164, v161
	v_rcp_iflag_f32_e32 v160, v160
	v_rcp_iflag_f32_e32 v161, v162
	v_rcp_iflag_f32_e32 v162, v163
	v_rcp_iflag_f32_e32 v163, v164
	v_cvt_f32_ubyte3_e32 v165, v156
	v_cvt_f32_ubyte2_e32 v164, v156
	v_cvt_f32_ubyte1_e32 v167, v156
	v_cvt_f32_ubyte0_e32 v166, v156
	v_pk_mul_f32 v[154:155], v[154:155], v[166:167]
	v_pk_mul_f32 v[158:159], v[158:159], v[164:165]
	v_pk_mul_f32 v[54:55], v[54:55], v[154:155]
	v_pk_mul_f32 v[56:57], v[56:57], v[158:159]
	v_cvt_f32_ubyte3_e32 v155, v157
	v_cvt_f32_ubyte2_e32 v154, v157
	v_cvt_f32_ubyte1_e32 v159, v157
	v_cvt_f32_ubyte0_e32 v158, v157
	v_pk_mul_f32 v[156:157], v[160:161], v[158:159]
	v_pk_mul_f32 v[154:155], v[162:163], v[154:155]
	v_pk_mul_f32 v[50:51], v[50:51], v[156:157]
	v_pk_mul_f32 v[52:53], v[52:53], v[154:155]
	s_waitcnt vmcnt(4)
	v_cvt_f32_ubyte0_e32 v0, v150
	v_cvt_f32_ubyte1_e32 v154, v150
	v_cvt_f32_ubyte2_e32 v155, v150
	v_cvt_f32_ubyte3_e32 v156, v150
	v_cvt_f32_ubyte0_e32 v157, v151
	v_cvt_f32_ubyte1_e32 v158, v151
	v_cvt_f32_ubyte2_e32 v159, v151
	v_cvt_f32_ubyte3_e32 v160, v151
	v_rcp_iflag_f32_e32 v150, v0
	v_rcp_iflag_f32_e32 v151, v154
	v_rcp_iflag_f32_e32 v154, v155
	v_rcp_iflag_f32_e32 v155, v156
	v_rcp_iflag_f32_e32 v156, v157
	v_rcp_iflag_f32_e32 v157, v158
	v_rcp_iflag_f32_e32 v158, v159
	v_rcp_iflag_f32_e32 v159, v160
	v_cvt_f32_ubyte3_e32 v161, v146
	v_cvt_f32_ubyte2_e32 v160, v146
	v_cvt_f32_ubyte1_e32 v163, v146
	v_cvt_f32_ubyte0_e32 v162, v146
	v_pk_mul_f32 v[150:151], v[150:151], v[162:163]
	v_pk_mul_f32 v[154:155], v[154:155], v[160:161]
	v_pk_mul_f32 v[46:47], v[46:47], v[150:151]
	v_pk_mul_f32 v[48:49], v[48:49], v[154:155]
	v_cvt_f32_ubyte3_e32 v151, v147
	v_cvt_f32_ubyte2_e32 v150, v147
	v_cvt_f32_ubyte1_e32 v155, v147
	v_cvt_f32_ubyte0_e32 v154, v147
	v_pk_mul_f32 v[146:147], v[156:157], v[154:155]
	v_pk_mul_f32 v[150:151], v[158:159], v[150:151]
	v_pk_mul_f32 v[42:43], v[42:43], v[146:147]
	v_pk_mul_f32 v[44:45], v[44:45], v[150:151]
	v_cvt_f32_ubyte0_e32 v0, v152
	v_cvt_f32_ubyte1_e32 v147, v152
	v_cvt_f32_ubyte2_e32 v150, v152
	v_cvt_f32_ubyte3_e32 v151, v152
	v_rcp_iflag_f32_e32 v146, v0
	v_rcp_iflag_f32_e32 v147, v147
	v_rcp_iflag_f32_e32 v150, v150
	v_rcp_iflag_f32_e32 v151, v151
	v_cvt_f32_ubyte0_e32 v152, v153
	v_cvt_f32_ubyte1_e32 v154, v153
	v_cvt_f32_ubyte2_e32 v155, v153
	v_cvt_f32_ubyte3_e32 v156, v153
	v_rcp_iflag_f32_e32 v152, v152
	v_rcp_iflag_f32_e32 v153, v154
	v_rcp_iflag_f32_e32 v154, v155
	v_rcp_iflag_f32_e32 v155, v156
	v_cvt_f32_ubyte3_e32 v157, v148
	v_cvt_f32_ubyte2_e32 v156, v148
	v_cvt_f32_ubyte1_e32 v159, v148
	v_cvt_f32_ubyte0_e32 v158, v148
	v_pk_mul_f32 v[146:147], v[146:147], v[158:159]
	v_pk_mul_f32 v[150:151], v[150:151], v[156:157]
	v_pk_mul_f32 v[38:39], v[38:39], v[146:147]
	v_pk_mul_f32 v[40:41], v[40:41], v[150:151]
	v_cvt_f32_ubyte3_e32 v147, v149
	v_cvt_f32_ubyte2_e32 v146, v149
	v_cvt_f32_ubyte1_e32 v151, v149
	v_cvt_f32_ubyte0_e32 v150, v149
	v_pk_mul_f32 v[148:149], v[152:153], v[150:151]
	v_pk_mul_f32 v[146:147], v[154:155], v[146:147]
	v_pk_mul_f32 v[34:35], v[34:35], v[148:149]
	v_pk_mul_f32 v[36:37], v[36:37], v[146:147]
	s_waitcnt vmcnt(2)
;     __device__ __forceinline__ void mid(Acc& acc, const Unit& u, int s, int wr, int wc, int fr, int fq) const {
;     ...
;         for (int i = 0; i < 8; ++i) { const int ai = i >> 2, m = i & 3;
; #pragma unroll
;             for (int bj = 0; bj < 2; ++bj) {
;                 const u32x4 ga = G[i][0], gb = G[i][1];
;                 const u32x2 wa = bj == 0 ? (u32x2){ga.x, ga.y} : (u32x2){ga.z, ga.w}, wb = bj == 0 ? (u32x2){gb.x, gb.y} : (u32x2){gb.z, gb.w};
;                 float fa[8], fb[8]; gate_unpack8(wa, fa); gate_unpack8(wb, fb);
; #pragma unroll
;                 for (int e = 0; e < 8; ++e) fa[e] = fa[e] * __builtin_amdgcn_rcpf(fb[e]);
;                 f32x4& v0 = acc[ai][bj][m][0]; f32x4& v1 = acc[ai][bj][m][1];
;                 v0[0] *= fa[0]; v0[1] *= fa[1]; v0[2] *= fa[2]; v0[3] *= fa[3]; v1[0] *= fa[4]; v1[1] *= fa[5]; v1[2] *= fa[6]; v1[3] *= fa[7]; }
	v_cvt_f32_ubyte0_e32 v0, v142
	v_cvt_f32_ubyte1_e32 v146, v142
	v_cvt_f32_ubyte2_e32 v147, v142
	v_cvt_f32_ubyte3_e32 v148, v142
	v_cvt_f32_ubyte0_e32 v149, v143
	v_cvt_f32_ubyte1_e32 v150, v143
	v_cvt_f32_ubyte2_e32 v151, v143
	v_cvt_f32_ubyte3_e32 v152, v143
	v_rcp_iflag_f32_e32 v142, v0
	v_rcp_iflag_f32_e32 v143, v146
	v_rcp_iflag_f32_e32 v146, v147
	v_rcp_iflag_f32_e32 v147, v148
	v_rcp_iflag_f32_e32 v148, v149
	v_rcp_iflag_f32_e32 v149, v150
	v_rcp_iflag_f32_e32 v150, v151
	v_rcp_iflag_f32_e32 v151, v152
	v_cvt_f32_ubyte3_e32 v153, v138
	v_cvt_f32_ubyte2_e32 v152, v138
	v_cvt_f32_ubyte1_e32 v155, v138
	v_cvt_f32_ubyte0_e32 v154, v138
	v_pk_mul_f32 v[142:143], v[142:143], v[154:155]
	v_pk_mul_f32 v[146:147], v[146:147], v[152:153]
	v_pk_mul_f32 v[30:31], v[30:31], v[142:143]
	v_pk_mul_f32 v[32:33], v[32:33], v[146:147]
	v_cvt_f32_ubyte3_e32 v143, v139
	v_cvt_f32_ubyte2_e32 v142, v139
	v_cvt_f32_ubyte1_e32 v147, v139
	v_cvt_f32_ubyte0_e32 v146, v139
	v_pk_mul_f32 v[138:139], v[148:149], v[146:147]
	v_pk_mul_f32 v[142:143], v[150:151], v[142:143]
	v_pk_mul_f32 v[22:23], v[22:23], v[138:139]
	v_pk_mul_f32 v[24:25], v[24:25], v[142:143]
	v_cvt_f32_ubyte0_e32 v0, v144
	v_cvt_f32_ubyte1_e32 v139, v144
	v_cvt_f32_ubyte2_e32 v142, v144
	v_cvt_f32_ubyte3_e32 v143, v144
	v_rcp_iflag_f32_e32 v138, v0
	v_rcp_iflag_f32_e32 v139, v139
	v_rcp_iflag_f32_e32 v142, v142
	v_rcp_iflag_f32_e32 v143, v143
	v_cvt_f32_ubyte0_e32 v144, v145
	v_cvt_f32_ubyte1_e32 v146, v145
	v_cvt_f32_ubyte2_e32 v147, v145
	v_cvt_f32_ubyte3_e32 v148, v145
	v_rcp_iflag_f32_e32 v144, v144
	v_rcp_iflag_f32_e32 v145, v146
	v_rcp_iflag_f32_e32 v146, v147
	v_rcp_iflag_f32_e32 v147, v148
	v_cvt_f32_ubyte3_e32 v149, v140
	v_cvt_f32_ubyte2_e32 v148, v140
	v_cvt_f32_ubyte1_e32 v151, v140
	v_cvt_f32_ubyte0_e32 v150, v140
	v_pk_mul_f32 v[138:139], v[138:139], v[150:151]
	v_pk_mul_f32 v[142:143], v[142:143], v[148:149]
	v_pk_mul_f32 v[26:27], v[26:27], v[138:139]
	v_pk_mul_f32 v[28:29], v[28:29], v[142:143]
	v_cvt_f32_ubyte3_e32 v139, v141
	v_cvt_f32_ubyte2_e32 v138, v141
	v_cvt_f32_ubyte1_e32 v143, v141
	v_cvt_f32_ubyte0_e32 v142, v141
	v_pk_mul_f32 v[140:141], v[144:145], v[142:143]
	v_pk_mul_f32 v[138:139], v[146:147], v[138:139]
	v_pk_mul_f32 v[18:19], v[18:19], v[140:141]
	v_pk_mul_f32 v[20:21], v[20:21], v[138:139]
	s_waitcnt vmcnt(0)
	v_cvt_f32_ubyte0_e32 v0, v134
	v_cvt_f32_ubyte1_e32 v138, v134
	v_cvt_f32_ubyte2_e32 v139, v134
	v_cvt_f32_ubyte3_e32 v140, v134
	v_cvt_f32_ubyte0_e32 v141, v135
	v_cvt_f32_ubyte1_e32 v142, v135
	v_cvt_f32_ubyte2_e32 v143, v135
	v_cvt_f32_ubyte3_e32 v144, v135
	v_rcp_iflag_f32_e32 v134, v0
	v_rcp_iflag_f32_e32 v135, v138
	v_rcp_iflag_f32_e32 v138, v139
	v_rcp_iflag_f32_e32 v139, v140
	v_rcp_iflag_f32_e32 v140, v141
	v_rcp_iflag_f32_e32 v141, v142
	v_rcp_iflag_f32_e32 v142, v143
	v_rcp_iflag_f32_e32 v143, v144
	v_cvt_f32_ubyte3_e32 v145, v130
	v_cvt_f32_ubyte2_e32 v144, v130
	v_cvt_f32_ubyte1_e32 v147, v130
	v_cvt_f32_ubyte0_e32 v146, v130
	v_pk_mul_f32 v[134:135], v[134:135], v[146:147]
	v_pk_mul_f32 v[138:139], v[138:139], v[144:145]
	v_pk_mul_f32 v[14:15], v[14:15], v[134:135]
	v_pk_mul_f32 v[16:17], v[16:17], v[138:139]
	v_cvt_f32_ubyte3_e32 v135, v131
	v_cvt_f32_ubyte2_e32 v134, v131
	v_cvt_f32_ubyte1_e32 v139, v131
	v_cvt_f32_ubyte0_e32 v138, v131
	v_pk_mul_f32 v[130:131], v[140:141], v[138:139]
	v_pk_mul_f32 v[134:135], v[142:143], v[134:135]
	v_pk_mul_f32 v[6:7], v[6:7], v[130:131]
	v_pk_mul_f32 v[8:9], v[8:9], v[134:135]
	v_cvt_f32_ubyte0_e32 v0, v136
	v_cvt_f32_ubyte1_e32 v131, v136
	v_cvt_f32_ubyte2_e32 v134, v136
	v_cvt_f32_ubyte3_e32 v135, v136
	v_rcp_iflag_f32_e32 v130, v0
	v_rcp_iflag_f32_e32 v131, v131
	v_rcp_iflag_f32_e32 v134, v134
	v_rcp_iflag_f32_e32 v135, v135
	v_cvt_f32_ubyte0_e32 v136, v137
	v_cvt_f32_ubyte1_e32 v138, v137
	v_cvt_f32_ubyte2_e32 v139, v137
	v_cvt_f32_ubyte3_e32 v140, v137
	v_rcp_iflag_f32_e32 v136, v136
	v_rcp_iflag_f32_e32 v137, v138
	v_rcp_iflag_f32_e32 v138, v139
	v_rcp_iflag_f32_e32 v139, v140
	v_cvt_f32_ubyte3_e32 v141, v132
	v_cvt_f32_ubyte2_e32 v140, v132
	v_cvt_f32_ubyte1_e32 v143, v132
	v_cvt_f32_ubyte0_e32 v142, v132
	v_pk_mul_f32 v[130:131], v[130:131], v[142:143]
	v_pk_mul_f32 v[134:135], v[134:135], v[140:141]
	v_pk_mul_f32 v[10:11], v[10:11], v[130:131]
	v_pk_mul_f32 v[12:13], v[12:13], v[134:135]
	v_cvt_f32_ubyte3_e32 v131, v133
	v_cvt_f32_ubyte2_e32 v130, v133
	v_cvt_f32_ubyte1_e32 v135, v133
	v_cvt_f32_ubyte0_e32 v134, v133
	v_pk_mul_f32 v[132:133], v[136:137], v[134:135]
	v_pk_mul_f32 v[130:131], v[138:139], v[130:131]
	v_pk_mul_f32 v[2:3], v[2:3], v[132:133]
	v_pk_mul_f32 v[4:5], v[4:5], v[130:131]

; #define PG8_STAGE(bufoff, gbase, voff) do { _Pragma("unroll") for (int _i = 0; _i < 2; ++_i) \
;         __builtin_amdgcn_global_load_lds((const unsigned*)((const char*)(gbase) + (voff)[_i]), (LAS unsigned*)(lds + (bufoff) + ldsw + _i * 8192), 16, 0, 0); } while (0)
; #define PG8_LDA(dst, b, h) do { _Pragma("unroll") for (int m = 0; m < 4; ++m) _Pragma("unroll") for (int k = 0; k < 2; ++k) dst[m][k] = *(const LAS bf16x8*)(lds + PG8_SA(b, h) + aoffk[k] + m * 2048); } while (0)
; #define PG8_LDB(dst, b, h) do { _Pragma("unroll") for (int n = 0; n < 2; ++n) _Pragma("unroll") for (int k = 0; k < 2; ++k) dst[n][k] = *(const LAS bf16x8*)(lds + PG8_SB(b, h) + boffk[k] + n * 2048); } while (0)
; #define PG8_WAIT_V(n) asm volatile("s_waitcnt vmcnt(" #n ")" ::: "memory")
; #define PG8_WAIT_L(n) asm volatile("s_waitcnt lgkmcnt(" #n ")" ::: "memory")
; #define PG8_BAR __builtin_amdgcn_s_barrier()
; #define PG8_SCHED __builtin_amdgcn_sched_barrier(0)
; template <class Epi, class Sched, class GemmT>
; __device__ __forceinline__ void gemm_phase(LAS unsigned char* lds, const GemmT& g, const Sched& S, const Epi& E, const int wid) {
;     ...
;             for (int t = 0; t < nt; t += 2) {
;                 const bool last = (t == nt - 2);
;                 const char* a1 = cA + (size_t)(t + 1) * kstep;
;                 const char* a2 = last ? ns.A : cA + (size_t)(t + 2) * kstep; const char* b2 = last ? ns.B : cB + (size_t)(t + 2) * kstep;
;                 const char* a3 = a2 + kstep; const char* b3 = b2 + kstep;
;                 unsigned vA2[2], vB2[2];
; #pragma unroll
;                 for (int i = 0; i < 2; ++i) { vA2[i] = last ? nvA[i] : voffA[i]; vB2[i] = last ? nvB[i] : voffB[i]; }
;                 const size_t hA2 = last ? nhA : hstepA, hB2 = last ? nhB : hstepB;
;                 PG8_LDB(B0, 0, 0); PG8_LDB(B1, 0, 1); PG8_SCHED; PG8_LDA(At, 0, 0); PG8_STAGE(PG8_SA(1, 1), a1 + hstepA, voffA);
;                 PG8_WAIT_V(8); PG8_WAIT_L(0); PG8_BAR; PG8_MMA(0, 0, At, B0); PG8_MMA(0, 1, At, B1); PG8_BAR; PG8_SCHED;
;     ...
; #pragma unroll
;         for (int a = 0; a < 2; ++a)
; #pragma unroll
;             for (int b = 0; b < 2; ++b)
; #pragma unroll
;                 for (int m = 0; m < 4; ++m)
; #pragma unroll
;                     for (int n = 0; n < 2; ++n) acc[a][b][m][n] = (f32x4){0.f, 0.f, 0.f, 0.f};
;         cur = nxt; ++ui;
.LBB0_845:
	s_ashr_i32 s37, s36, 31
	s_ashr_i32 s39, s38, 31
	s_lshl_b64 s[36:37], s[36:37], 21
	s_add_u32 s36, s10, s36
	s_addc_u32 s37, s11, s37
	s_lshl_b64 s[38:39], s[38:39], 21
	s_add_u32 s41, s72, s38
	s_addc_u32 s59, s73, s39
	s_add_u32 s42, s42, 0x100080
	s_addc_u32 s43, s43, 0
	s_add_u32 s60, s52, s44
	v_mov_b32_e32 v0, 0
	s_addc_u32 s61, s53, s45
	s_mov_b32 s62, -2
	v_mov_b32_e32 v1, v0
	v_mov_b32_e32 v2, v0
	v_mov_b32_e32 v3, v0
	v_mov_b32_e32 v4, v0
	v_mov_b32_e32 v5, v0
	v_mov_b32_e32 v6, v0
	v_mov_b32_e32 v7, v0
	v_mov_b32_e32 v16, v0
	v_mov_b32_e32 v17, v0
	v_mov_b32_e32 v18, v0
	v_mov_b32_e32 v19, v0
	v_mov_b32_e32 v20, v0
	v_mov_b32_e32 v21, v0
	v_mov_b32_e32 v22, v0
	v_mov_b32_e32 v23, v0
	v_mov_b32_e32 v32, v0
	v_mov_b32_e32 v33, v0
	v_mov_b32_e32 v34, v0
	v_mov_b32_e32 v35, v0
	v_mov_b32_e32 v36, v0
	v_mov_b32_e32 v37, v0
	v_mov_b32_e32 v38, v0
	v_mov_b32_e32 v39, v0
	v_mov_b32_e32 v48, v0
	v_mov_b32_e32 v49, v0
	v_mov_b32_e32 v50, v0
	v_mov_b32_e32 v51, v0
	v_mov_b32_e32 v52, v0
	v_mov_b32_e32 v53, v0
	v_mov_b32_e32 v54, v0
	v_mov_b32_e32 v55, v0
	v_mov_b32_e32 v64, v0
	v_mov_b32_e32 v65, v0
	v_mov_b32_e32 v66, v0
	v_mov_b32_e32 v67, v0
	v_mov_b32_e32 v68, v0
	v_mov_b32_e32 v69, v0
	v_mov_b32_e32 v70, v0
	v_mov_b32_e32 v71, v0
	v_mov_b32_e32 v80, v0
	v_mov_b32_e32 v81, v0
	v_mov_b32_e32 v82, v0
	v_mov_b32_e32 v83, v0
	v_mov_b32_e32 v84, v0
	v_mov_b32_e32 v85, v0
	v_mov_b32_e32 v86, v0
	v_mov_b32_e32 v87, v0
	v_mov_b32_e32 v96, v0
	v_mov_b32_e32 v97, v0
	v_mov_b32_e32 v98, v0
	v_mov_b32_e32 v99, v0
	v_mov_b32_e32 v100, v0
	v_mov_b32_e32 v101, v0
	v_mov_b32_e32 v102, v0
	v_mov_b32_e32 v103, v0
	v_mov_b32_e32 v112, v0
	v_mov_b32_e32 v113, v0
	v_mov_b32_e32 v114, v0
	v_mov_b32_e32 v115, v0
	v_mov_b32_e32 v116, v0
	v_mov_b32_e32 v117, v0
	v_mov_b32_e32 v118, v0
	v_mov_b32_e32 v119, v0
	v_mov_b32_e32 v72, v0
	v_mov_b32_e32 v73, v0
	v_mov_b32_e32 v74, v0
	v_mov_b32_e32 v75, v0
	v_mov_b32_e32 v76, v0
	v_mov_b32_e32 v77, v0
	v_mov_b32_e32 v78, v0
	v_mov_b32_e32 v79, v0
	v_mov_b32_e32 v88, v0
	v_mov_b32_e32 v89, v0
	v_mov_b32_e32 v90, v0
	v_mov_b32_e32 v91, v0
	v_mov_b32_e32 v92, v0
	v_mov_b32_e32 v93, v0
	v_mov_b32_e32 v94, v0
	v_mov_b32_e32 v95, v0
	v_mov_b32_e32 v104, v0
	v_mov_b32_e32 v105, v0
	v_mov_b32_e32 v106, v0
	v_mov_b32_e32 v107, v0
	v_mov_b32_e32 v108, v0
	v_mov_b32_e32 v109, v0
	v_mov_b32_e32 v110, v0
	v_mov_b32_e32 v111, v0
	v_mov_b32_e32 v120, v0
	v_mov_b32_e32 v121, v0
	v_mov_b32_e32 v122, v0
	v_mov_b32_e32 v123, v0
	v_mov_b32_e32 v124, v0
	v_mov_b32_e32 v125, v0
	v_mov_b32_e32 v126, v0
	v_mov_b32_e32 v127, v0
	v_mov_b32_e32 v60, v0
	v_mov_b32_e32 v61, v0
	v_mov_b32_e32 v62, v0
	v_mov_b32_e32 v63, v0
	v_mov_b32_e32 v56, v0
	v_mov_b32_e32 v57, v0
	v_mov_b32_e32 v58, v0
	v_mov_b32_e32 v59, v0
	v_mov_b32_e32 v44, v0
	v_mov_b32_e32 v45, v0
	v_mov_b32_e32 v46, v0
	v_mov_b32_e32 v47, v0
	v_mov_b32_e32 v40, v0
	v_mov_b32_e32 v41, v0
	v_mov_b32_e32 v42, v0
	v_mov_b32_e32 v43, v0
	v_mov_b32_e32 v28, v0
	v_mov_b32_e32 v29, v0
	v_mov_b32_e32 v30, v0
	v_mov_b32_e32 v31, v0
	v_mov_b32_e32 v24, v0
	v_mov_b32_e32 v25, v0
	v_mov_b32_e32 v26, v0
	v_mov_b32_e32 v27, v0
	v_mov_b32_e32 v12, v0
	v_mov_b32_e32 v13, v0
	v_mov_b32_e32 v14, v0
	v_mov_b32_e32 v15, v0
	v_mov_b32_e32 v8, v0
	v_mov_b32_e32 v9, v0
	v_mov_b32_e32 v10, v0
	v_mov_b32_e32 v11, v0
	s_nop 0
.LBB0_846:
	ds_read_b128 v[128:131], v194
	ds_read_b128 v[132:135], v195
	ds_read_b128 v[136:139], v196
	ds_read_b128 v[140:143], v197
	ds_read_b128 v[144:147], v198
	ds_read_b128 v[148:151], v199
	ds_read_b128 v[152:155], v200
	ds_read_b128 v[168:171], v201
	s_add_u32 s44, s42, 0xfff00080
	s_addc_u32 s45, s43, -1
	s_cmp_eq_u32 s62, 60
	s_cselect_b32 s51, s37, s45
	s_cselect_b32 s50, s36, s44
	s_cselect_b32 s45, s59, s61
	s_cselect_b32 s44, s41, s60
	v_lshl_add_u64 v[188:189], s[42:43], 0, v[156:157]
	s_add_i32 m0, s14, 0xc000
	ds_read_b128 v[172:175], v202
	ds_read_b128 v[176:179], v202 offset:2048
	ds_read_b128 v[180:183], v203
	ds_read_b128 v[184:187], v203 offset:2048
	ds_read_b128 v[208:211], v202 offset:4096
	ds_read_b128 v[212:215], v202 offset:6144
	ds_read_b128 v[216:219], v203 offset:4096
	ds_read_b128 v[220:223], v203 offset:6144
	global_load_lds_dwordx4 v[188:189], off
	v_lshl_add_u64 v[188:189], s[42:43], 0, v[160:161]
	s_add_i32 m0, s14, 0xe000
	s_nop 0
	global_load_lds_dwordx4 v[188:189], off
	s_waitcnt vmcnt(8)
	s_waitcnt lgkmcnt(0)
	s_barrier
	s_setprio 3
	s_waitcnt lgkmcnt(0)
	v_mfma_f32_16x16x32_bf16 v[124:127], v[128:131], v[172:175], v[124:127]
	v_mfma_f32_16x16x32_bf16 v[124:127], v[132:135], v[180:183], v[124:127]
	v_mfma_f32_16x16x32_bf16 v[120:123], v[140:143], v[180:183], v[120:123]
	v_mfma_f32_16x16x32_bf16 v[120:123], v[136:139], v[172:175], v[120:123]
	v_mfma_f32_16x16x32_bf16 v[104:107], v[136:139], v[176:179], v[104:107]
	v_mfma_f32_16x16x32_bf16 v[104:107], v[140:143], v[184:187], v[104:107]
	v_mfma_f32_16x16x32_bf16 v[108:111], v[132:135], v[184:187], v[108:111]
	v_mfma_f32_16x16x32_bf16 v[108:111], v[128:131], v[176:179], v[108:111]
	v_mfma_f32_16x16x32_bf16 v[92:95], v[128:131], v[208:211], v[92:95]
	v_mfma_f32_16x16x32_bf16 v[92:95], v[132:135], v[216:219], v[92:95]
	v_mfma_f32_16x16x32_bf16 v[88:91], v[140:143], v[216:219], v[88:91]
	v_mfma_f32_16x16x32_bf16 v[88:91], v[136:139], v[208:211], v[88:91]
	v_mfma_f32_16x16x32_bf16 v[72:75], v[136:139], v[212:215], v[72:75]
	v_mfma_f32_16x16x32_bf16 v[72:75], v[140:143], v[220:223], v[72:75]
	v_mfma_f32_16x16x32_bf16 v[76:79], v[132:135], v[220:223], v[76:79]
	v_mfma_f32_16x16x32_bf16 v[76:79], v[128:131], v[212:215], v[76:79]
	s_setprio 0
	s_setprio 3
	v_mfma_f32_16x16x32_bf16 v[116:119], v[144:147], v[172:175], v[116:119]
	v_mfma_f32_16x16x32_bf16 v[116:119], v[148:151], v[180:183], v[116:119]
	v_mfma_f32_16x16x32_bf16 v[112:115], v[168:171], v[180:183], v[112:115]
	v_mfma_f32_16x16x32_bf16 v[112:115], v[152:155], v[172:175], v[112:115]
	v_mfma_f32_16x16x32_bf16 v[96:99], v[152:155], v[176:179], v[96:99]
	v_mfma_f32_16x16x32_bf16 v[96:99], v[168:171], v[184:187], v[96:99]
	v_mfma_f32_16x16x32_bf16 v[100:103], v[148:151], v[184:187], v[100:103]
	v_mfma_f32_16x16x32_bf16 v[100:103], v[144:147], v[176:179], v[100:103]
	v_mfma_f32_16x16x32_bf16 v[84:87], v[144:147], v[208:211], v[84:87]
	v_mfma_f32_16x16x32_bf16 v[84:87], v[148:151], v[216:219], v[84:87]
	v_mfma_f32_16x16x32_bf16 v[80:83], v[168:171], v[216:219], v[80:83]
	v_mfma_f32_16x16x32_bf16 v[80:83], v[152:155], v[208:211], v[80:83]
	v_mfma_f32_16x16x32_bf16 v[64:67], v[152:155], v[212:215], v[64:67]
	v_mfma_f32_16x16x32_bf16 v[64:67], v[168:171], v[220:223], v[64:67]
	v_mfma_f32_16x16x32_bf16 v[68:71], v[148:151], v[220:223], v[68:71]
	v_mfma_f32_16x16x32_bf16 v[68:71], v[144:147], v[212:215], v[68:71]
	s_setprio 0
	s_barrier
; #define PG8_STAGE(bufoff, gbase, voff) do { _Pragma("unroll") for (int _i = 0; _i < 2; ++_i) \
;         __builtin_amdgcn_global_load_lds((const unsigned*)((const char*)(gbase) + (voff)[_i]), (LAS unsigned*)(lds + (bufoff) + ldsw + _i * 8192), 16, 0, 0); } while (0)
; #define PG8_LDA(dst, b, h) do { _Pragma("unroll") for (int m = 0; m < 4; ++m) _Pragma("unroll") for (int k = 0; k < 2; ++k) dst[m][k] = *(const LAS bf16x8*)(lds + PG8_SA(b, h) + aoffk[k] + m * 2048); } while (0)
; #define PG8_LDB(dst, b, h) do { _Pragma("unroll") for (int n = 0; n < 2; ++n) _Pragma("unroll") for (int k = 0; k < 2; ++k) dst[n][k] = *(const LAS bf16x8*)(lds + PG8_SB(b, h) + boffk[k] + n * 2048); } while (0)
; #define PG8_WAIT_V(n) asm volatile("s_waitcnt vmcnt(" #n ")" ::: "memory")
; #define PG8_WAIT_L(n) asm volatile("s_waitcnt lgkmcnt(" #n ")" ::: "memory")
; #define PG8_BAR __builtin_amdgcn_s_barrier()
; #define PG8_SCHED __builtin_amdgcn_sched_barrier(0)
; template <class Epi, class Sched, class GemmT>
; __device__ __forceinline__ void gemm_phase(LAS unsigned char* lds, const GemmT& g, const Sched& S, const Epi& E, const int wid) {
;     ...
;                 PG8_LDA(At, 0, 1); PG8_STAGE(PG8_SB(0, 0), b2, vB2); PG8_STAGE(PG8_SB(0, 1), b2 + hB2, vB2); PG8_STAGE(PG8_SA(0, 0), a2, vA2);
;                 PG8_WAIT_V(8); PG8_WAIT_L(0); PG8_BAR; PG8_MMA(1, 0, At, B0); PG8_MMA(1, 1, At, B1); PG8_BAR; PG8_SCHED;
;                 PG8_LDB(B0, 1, 0); PG8_LDB(B1, 1, 1); PG8_SCHED; PG8_LDA(At, 1, 0); PG8_STAGE(PG8_SA(0, 1), a2 + hA2, vA2);
	s_add_i32 s48, s54, s68
	v_lshl_add_u64 v[188:189], s[44:45], 0, v[158:159]
	s_mov_b32 m0, s48
	ds_read_b128 v[172:175], v202 offset:16384
	ds_read_b128 v[176:179], v202 offset:18432
	ds_read_b128 v[180:183], v203 offset:16384
	ds_read_b128 v[184:187], v203 offset:18432
	ds_read_b128 v[208:211], v202 offset:20480
	ds_read_b128 v[212:215], v202 offset:22528
	ds_read_b128 v[216:219], v203 offset:20480
	ds_read_b128 v[220:223], v203 offset:22528
	global_load_lds_dwordx4 v[188:189], off
	s_add_i32 m0, s48, 0x2000
	s_add_u32 s48, s44, 0x100000
	v_lshl_add_u64 v[224:225], s[44:45], 0, v[162:163]
	s_addc_u32 s49, s45, 0
	s_add_i32 s63, s55, s68
	global_load_lds_dwordx4 v[224:225], off
	v_lshl_add_u64 v[226:227], s[48:49], 0, v[158:159]
	s_mov_b32 m0, s63
	v_lshl_add_u64 v[230:231], s[50:51], 0, v[160:161]
	global_load_lds_dwordx4 v[226:227], off
	v_lshl_add_u64 v[226:227], s[48:49], 0, v[162:163]
	s_add_i32 m0, s63, 0x2000
	s_nop 0
	global_load_lds_dwordx4 v[226:227], off
	v_lshl_add_u64 v[226:227], s[50:51], 0, v[156:157]
	s_mov_b32 m0, s14
	s_nop 0
	global_load_lds_dwordx4 v[226:227], off
	s_mov_b32 m0, s15
	s_nop 0
	global_load_lds_dwordx4 v[230:231], off
	s_waitcnt vmcnt(8)
	s_waitcnt lgkmcnt(0)
	s_barrier
	s_setprio 3
	s_waitcnt lgkmcnt(0)
	v_mfma_f32_16x16x32_bf16 v[52:55], v[128:131], v[172:175], v[52:55]
	v_mfma_f32_16x16x32_bf16 v[52:55], v[132:135], v[180:183], v[52:55]
	v_mfma_f32_16x16x32_bf16 v[48:51], v[140:143], v[180:183], v[48:51]
	v_mfma_f32_16x16x32_bf16 v[48:51], v[136:139], v[172:175], v[48:51]
	v_mfma_f32_16x16x32_bf16 v[32:35], v[136:139], v[176:179], v[32:35]
	v_mfma_f32_16x16x32_bf16 v[32:35], v[140:143], v[184:187], v[32:35]
	v_mfma_f32_16x16x32_bf16 v[36:39], v[132:135], v[184:187], v[36:39]
	v_mfma_f32_16x16x32_bf16 v[36:39], v[128:131], v[176:179], v[36:39]
	v_mfma_f32_16x16x32_bf16 v[20:23], v[128:131], v[208:211], v[20:23]
	v_mfma_f32_16x16x32_bf16 v[20:23], v[132:135], v[216:219], v[20:23]
	v_mfma_f32_16x16x32_bf16 v[16:19], v[140:143], v[216:219], v[16:19]
	v_mfma_f32_16x16x32_bf16 v[16:19], v[136:139], v[208:211], v[16:19]
	v_mfma_f32_16x16x32_bf16 v[0:3], v[136:139], v[212:215], v[0:3]
	v_mfma_f32_16x16x32_bf16 v[0:3], v[140:143], v[220:223], v[0:3]
	v_mfma_f32_16x16x32_bf16 v[4:7], v[132:135], v[220:223], v[4:7]
	v_mfma_f32_16x16x32_bf16 v[4:7], v[128:131], v[212:215], v[4:7]
	s_setprio 0
	s_setprio 3
	v_mfma_f32_16x16x32_bf16 v[60:63], v[144:147], v[172:175], v[60:63]
	v_mfma_f32_16x16x32_bf16 v[60:63], v[148:151], v[180:183], v[60:63]
	v_mfma_f32_16x16x32_bf16 v[56:59], v[168:171], v[180:183], v[56:59]
	v_mfma_f32_16x16x32_bf16 v[56:59], v[152:155], v[172:175], v[56:59]
	v_mfma_f32_16x16x32_bf16 v[40:43], v[152:155], v[176:179], v[40:43]
	v_mfma_f32_16x16x32_bf16 v[40:43], v[168:171], v[184:187], v[40:43]
	v_mfma_f32_16x16x32_bf16 v[44:47], v[148:151], v[184:187], v[44:47]
	v_mfma_f32_16x16x32_bf16 v[44:47], v[144:147], v[176:179], v[44:47]
	v_mfma_f32_16x16x32_bf16 v[28:31], v[144:147], v[208:211], v[28:31]
	v_mfma_f32_16x16x32_bf16 v[28:31], v[148:151], v[216:219], v[28:31]
	v_mfma_f32_16x16x32_bf16 v[24:27], v[168:171], v[216:219], v[24:27]
	v_mfma_f32_16x16x32_bf16 v[24:27], v[152:155], v[208:211], v[24:27]
	v_mfma_f32_16x16x32_bf16 v[8:11], v[152:155], v[212:215], v[8:11]
	v_mfma_f32_16x16x32_bf16 v[8:11], v[168:171], v[220:223], v[8:11]
	v_mfma_f32_16x16x32_bf16 v[12:15], v[148:151], v[220:223], v[12:15]
	v_mfma_f32_16x16x32_bf16 v[12:15], v[144:147], v[212:215], v[12:15]
	s_setprio 0
	s_barrier
	s_add_i32 s63, 0, 0x18000
	s_add_i32 s64, 0, 0x1c000
	v_add_u32_e32 v128, s63, v191
	v_add_u32_e32 v132, s63, v192
	v_add_u32_e32 v144, s64, v191
	v_add_u32_e32 v148, s64, v192
	ds_read_b128 v[128:131], v128
	ds_read_b128 v[132:135], v132
	ds_read_b128 v[136:139], v204
	ds_read_b128 v[140:143], v205
	ds_read_b128 v[144:147], v144
	ds_read_b128 v[148:151], v148
	ds_read_b128 v[152:155], v206
	ds_read_b128 v[168:171], v207
	s_add_u32 s48, s50, 0x100000
	s_addc_u32 s49, s51, 0
	s_mov_b32 m0, s22
	v_lshl_add_u64 v[232:233], s[48:49], 0, v[156:157]
	ds_read_b128 v[172:175], v202 offset:32768
	ds_read_b128 v[176:179], v202 offset:34816
	ds_read_b128 v[180:183], v203 offset:32768
	ds_read_b128 v[184:187], v203 offset:34816
	ds_read_b128 v[208:211], v202 offset:36864
	ds_read_b128 v[212:215], v202 offset:38912
	ds_read_b128 v[216:219], v203 offset:36864
	ds_read_b128 v[220:223], v203 offset:38912
	global_load_lds_dwordx4 v[232:233], off
	v_lshl_add_u64 v[232:233], s[48:49], 0, v[160:161]
	s_mov_b32 m0, s23
	s_nop 0
	global_load_lds_dwordx4 v[232:233], off
	s_waitcnt vmcnt(8)
	s_waitcnt lgkmcnt(0)
	s_barrier
; #define PG8_STAGE(bufoff, gbase, voff) do { _Pragma("unroll") for (int _i = 0; _i < 2; ++_i) \
;         __builtin_amdgcn_global_load_lds((const unsigned*)((const char*)(gbase) + (voff)[_i]), (LAS unsigned*)(lds + (bufoff) + ldsw + _i * 8192), 16, 0, 0); } while (0)
; #define PG8_LDA(dst, b, h) do { _Pragma("unroll") for (int m = 0; m < 4; ++m) _Pragma("unroll") for (int k = 0; k < 2; ++k) dst[m][k] = *(const LAS bf16x8*)(lds + PG8_SA(b, h) + aoffk[k] + m * 2048); } while (0)
; #define PG8_WAIT_V(n) asm volatile("s_waitcnt vmcnt(" #n ")" ::: "memory")
; #define PG8_WAIT_L(n) asm volatile("s_waitcnt lgkmcnt(" #n ")" ::: "memory")
; #define PG8_BAR __builtin_amdgcn_s_barrier()
; #define PG8_SCHED __builtin_amdgcn_sched_barrier(0)
; template <class Epi, class Sched, class GemmT>
; __device__ __forceinline__ void gemm_phase(LAS unsigned char* lds, const GemmT& g, const Sched& S, const Epi& E, const int wid) {
;     ...
;                 PG8_WAIT_V(8); PG8_WAIT_L(0); PG8_BAR; PG8_MMA(0, 0, At, B0); PG8_MMA(0, 1, At, B1); PG8_BAR; PG8_SCHED;
;                 PG8_LDA(At, 1, 1); PG8_STAGE(PG8_SB(1, 0), b3, vB2); PG8_STAGE(PG8_SB(1, 1), b3 + hB2, vB2); PG8_STAGE(PG8_SA(1, 0), a3, vA2);
;                 PG8_WAIT_V(8); PG8_WAIT_L(0); PG8_BAR; PG8_MMA(1, 0, At, B0); PG8_MMA(1, 1, At, B1); PG8_BAR; PG8_SCHED;
;             }
	s_setprio 3
	s_waitcnt lgkmcnt(0)
	v_mfma_f32_16x16x32_bf16 v[124:127], v[128:131], v[172:175], v[124:127]
	v_mfma_f32_16x16x32_bf16 v[124:127], v[132:135], v[180:183], v[124:127]
	v_mfma_f32_16x16x32_bf16 v[120:123], v[140:143], v[180:183], v[120:123]
	v_mfma_f32_16x16x32_bf16 v[120:123], v[136:139], v[172:175], v[120:123]
	v_mfma_f32_16x16x32_bf16 v[104:107], v[136:139], v[176:179], v[104:107]
	v_mfma_f32_16x16x32_bf16 v[104:107], v[140:143], v[184:187], v[104:107]
	v_mfma_f32_16x16x32_bf16 v[108:111], v[132:135], v[184:187], v[108:111]
	v_mfma_f32_16x16x32_bf16 v[108:111], v[128:131], v[176:179], v[108:111]
	v_mfma_f32_16x16x32_bf16 v[92:95], v[128:131], v[208:211], v[92:95]
	v_mfma_f32_16x16x32_bf16 v[92:95], v[132:135], v[216:219], v[92:95]
	v_mfma_f32_16x16x32_bf16 v[88:91], v[140:143], v[216:219], v[88:91]
	v_mfma_f32_16x16x32_bf16 v[88:91], v[136:139], v[208:211], v[88:91]
	v_mfma_f32_16x16x32_bf16 v[72:75], v[136:139], v[212:215], v[72:75]
	v_mfma_f32_16x16x32_bf16 v[72:75], v[140:143], v[220:223], v[72:75]
	v_mfma_f32_16x16x32_bf16 v[76:79], v[132:135], v[220:223], v[76:79]
	v_mfma_f32_16x16x32_bf16 v[76:79], v[128:131], v[212:215], v[76:79]
	s_setprio 0
	s_setprio 3
	v_mfma_f32_16x16x32_bf16 v[116:119], v[144:147], v[172:175], v[116:119]
	v_mfma_f32_16x16x32_bf16 v[116:119], v[148:151], v[180:183], v[116:119]
	v_mfma_f32_16x16x32_bf16 v[112:115], v[168:171], v[180:183], v[112:115]
	v_mfma_f32_16x16x32_bf16 v[112:115], v[152:155], v[172:175], v[112:115]
	v_mfma_f32_16x16x32_bf16 v[96:99], v[152:155], v[176:179], v[96:99]
	v_mfma_f32_16x16x32_bf16 v[96:99], v[168:171], v[184:187], v[96:99]
	v_mfma_f32_16x16x32_bf16 v[100:103], v[148:151], v[184:187], v[100:103]
	v_mfma_f32_16x16x32_bf16 v[100:103], v[144:147], v[176:179], v[100:103]
	v_mfma_f32_16x16x32_bf16 v[84:87], v[144:147], v[208:211], v[84:87]
	v_mfma_f32_16x16x32_bf16 v[84:87], v[148:151], v[216:219], v[84:87]
	v_mfma_f32_16x16x32_bf16 v[80:83], v[168:171], v[216:219], v[80:83]
	v_mfma_f32_16x16x32_bf16 v[80:83], v[152:155], v[208:211], v[80:83]
	v_mfma_f32_16x16x32_bf16 v[64:67], v[152:155], v[212:215], v[64:67]
	v_mfma_f32_16x16x32_bf16 v[64:67], v[168:171], v[220:223], v[64:67]
	v_mfma_f32_16x16x32_bf16 v[68:71], v[148:151], v[220:223], v[68:71]
	v_mfma_f32_16x16x32_bf16 v[68:71], v[144:147], v[212:215], v[68:71]
	s_setprio 0
	s_barrier
	s_add_i32 s48, s63, s68
	v_lshl_add_u64 v[188:189], v[188:189], 0, s[18:19]
	s_mov_b32 m0, s48
	ds_read_b128 v[172:175], v202 offset:49152
	ds_read_b128 v[176:179], v202 offset:51200
	ds_read_b128 v[180:183], v203 offset:49152
	ds_read_b128 v[184:187], v203 offset:51200
	ds_read_b128 v[208:211], v202 offset:53248
	ds_read_b128 v[212:215], v202 offset:55296
	ds_read_b128 v[216:219], v203 offset:53248
	ds_read_b128 v[220:223], v203 offset:55296
	global_load_lds_dwordx4 v[188:189], off
	s_add_i32 m0, s48, 0x2000
	s_add_u32 s44, s44, 0x100080
	v_lshl_add_u64 v[188:189], v[224:225], 0, s[18:19]
	s_addc_u32 s45, s45, 0
	s_add_i32 s48, s64, s68
	global_load_lds_dwordx4 v[188:189], off
	v_lshl_add_u64 v[188:189], s[44:45], 0, v[158:159]
	s_mov_b32 m0, s48
	s_nop 0
	global_load_lds_dwordx4 v[188:189], off
	v_lshl_add_u64 v[188:189], s[44:45], 0, v[162:163]
	s_add_i32 m0, s48, 0x2000
	s_nop 0
	global_load_lds_dwordx4 v[188:189], off
	v_lshl_add_u64 v[188:189], v[226:227], 0, s[18:19]
	s_mov_b32 m0, s34
	s_nop 0
	global_load_lds_dwordx4 v[188:189], off
	v_lshl_add_u64 v[188:189], v[230:231], 0, s[18:19]
	s_mov_b32 m0, s35
	s_nop 0
	global_load_lds_dwordx4 v[188:189], off
	s_waitcnt vmcnt(8)
	s_waitcnt lgkmcnt(0)
	s_barrier
	s_setprio 3
	s_waitcnt lgkmcnt(0)
	v_mfma_f32_16x16x32_bf16 v[52:55], v[128:131], v[172:175], v[52:55]
	v_mfma_f32_16x16x32_bf16 v[52:55], v[132:135], v[180:183], v[52:55]
	v_mfma_f32_16x16x32_bf16 v[48:51], v[140:143], v[180:183], v[48:51]
	v_mfma_f32_16x16x32_bf16 v[48:51], v[136:139], v[172:175], v[48:51]
	v_mfma_f32_16x16x32_bf16 v[32:35], v[136:139], v[176:179], v[32:35]
	v_mfma_f32_16x16x32_bf16 v[32:35], v[140:143], v[184:187], v[32:35]
	v_mfma_f32_16x16x32_bf16 v[36:39], v[132:135], v[184:187], v[36:39]
	v_mfma_f32_16x16x32_bf16 v[36:39], v[128:131], v[176:179], v[36:39]
	v_mfma_f32_16x16x32_bf16 v[20:23], v[128:131], v[208:211], v[20:23]
	v_mfma_f32_16x16x32_bf16 v[20:23], v[132:135], v[216:219], v[20:23]
	v_mfma_f32_16x16x32_bf16 v[16:19], v[140:143], v[216:219], v[16:19]
	v_mfma_f32_16x16x32_bf16 v[16:19], v[136:139], v[208:211], v[16:19]
	v_mfma_f32_16x16x32_bf16 v[0:3], v[136:139], v[212:215], v[0:3]
	v_mfma_f32_16x16x32_bf16 v[0:3], v[140:143], v[220:223], v[0:3]
	v_mfma_f32_16x16x32_bf16 v[4:7], v[132:135], v[220:223], v[4:7]
	v_mfma_f32_16x16x32_bf16 v[4:7], v[128:131], v[212:215], v[4:7]
	s_setprio 0
	s_setprio 3
	v_mfma_f32_16x16x32_bf16 v[60:63], v[144:147], v[172:175], v[60:63]
	v_mfma_f32_16x16x32_bf16 v[60:63], v[148:151], v[180:183], v[60:63]
	v_mfma_f32_16x16x32_bf16 v[56:59], v[168:171], v[180:183], v[56:59]
	v_mfma_f32_16x16x32_bf16 v[56:59], v[152:155], v[172:175], v[56:59]
	v_mfma_f32_16x16x32_bf16 v[40:43], v[152:155], v[176:179], v[40:43]
	v_mfma_f32_16x16x32_bf16 v[40:43], v[168:171], v[184:187], v[40:43]
	v_mfma_f32_16x16x32_bf16 v[44:47], v[148:151], v[184:187], v[44:47]
	v_mfma_f32_16x16x32_bf16 v[44:47], v[144:147], v[176:179], v[44:47]
	v_mfma_f32_16x16x32_bf16 v[28:31], v[144:147], v[208:211], v[28:31]
	v_mfma_f32_16x16x32_bf16 v[28:31], v[148:151], v[216:219], v[28:31]
	v_mfma_f32_16x16x32_bf16 v[24:27], v[168:171], v[216:219], v[24:27]
	v_mfma_f32_16x16x32_bf16 v[24:27], v[152:155], v[208:211], v[24:27]
	v_mfma_f32_16x16x32_bf16 v[8:11], v[152:155], v[212:215], v[8:11]
	v_mfma_f32_16x16x32_bf16 v[8:11], v[168:171], v[220:223], v[8:11]
	v_mfma_f32_16x16x32_bf16 v[12:15], v[148:151], v[220:223], v[12:15]
	v_mfma_f32_16x16x32_bf16 v[12:15], v[144:147], v[212:215], v[12:15]
	s_setprio 0
	s_barrier
	s_add_i32 s62, s62, 2
	s_add_u32 s42, s42, 0x100
	s_addc_u32 s43, s43, 0
	s_add_u32 s60, s60, 0x100
	s_addc_u32 s61, s61, 0
	s_cmp_gt_u32 s62, 61
	s_cbranch_scc0 .LBB0_846
	s_nop 0
	s_and_b64 vcc, exec, s[20:21]
	s_cbranch_vccz .LBB0_849
	s_barrier
